# plus SSD state-update ring-buffered B reads and QKV V-transposed stores via in-quad DPP transpose (dwordx2 instead of 4 short stores)
# baseline (speedup 1.0000x reference)
; #define PG8_STAGE(bufoff, gbase) do { _Pragma("unroll") for (int _i = 0; _i < 2; ++_i) \
;     __builtin_amdgcn_global_load_lds((const unsigned*)((const char*)(gbase) + voff[_i]), (LAS unsigned*)(lds + (bufoff) + ldsw + _i * 8192), 16, 0, 0); } while (0)
; #define PG8_LDA(dst, b, h) do { _Pragma("unroll") for (int m = 0; m < 4; ++m) _Pragma("unroll") for (int k = 0; k < 2; ++k) dst[m][k] = *(const LAS bf16x8*)(lds + PG8_SA(b, h) + aoff + m * 2048 + k * 1024); } while (0)
; #define PG8_LDB(dst, b, h) do { _Pragma("unroll") for (int n = 0; n < 2; ++n) _Pragma("unroll") for (int k = 0; k < 2; ++k) dst[n][k] = *(const LAS bf16x8*)(lds + PG8_SB(b, h) + boff + n * 2048 + k * 1024); } while (0)
; #define PG8_MMA(ai, bj, At, Bt_) do { __builtin_amdgcn_s_setprio(1); _Pragma("unroll") for (int m = 0; m < 4; ++m) _Pragma("unroll") for (int n = 0; n < 2; ++n) _Pragma("unroll") for (int k = 0; k < 2; ++k) \
;     acc[ai][bj][m][n] = __builtin_amdgcn_mfma_f32_16x16x32_bf16(Bt_[n][k], At[m][k], acc[ai][bj][m][n], 0, 0, 0); __builtin_amdgcn_s_setprio(0); } while (0)
; #define PG8_WAIT_L(n) asm volatile("s_waitcnt lgkmcnt(" #n ")" ::: "memory")
; #define PG8_BAR __builtin_amdgcn_s_barrier()
; #define PG8_SCHED __builtin_amdgcn_sched_barrier(0)
; template <int EPI>
; __device__ __forceinline__ void gemm_phase(KP P, const bfu* __restrict__ A, const bfu* __restrict__ Bt, int K, int ntn, char* smem, const int wv) {
;     ...
;       PG8_LDB(B0, 0, 0); PG8_SCHED; PG8_LDA(At, 0, 0); PG8_STAGE(PG8_SA(1, 1), a1 + hstep);
;       PG8_WAIT_L(8); PG8_BAR; PG8_WAIT_L(0); PG8_MMA(0, 0, At, B0); PG8_BAR; PG8_SCHED;
;       PG8_LDB(B1, 0, 1); PG8_STAGE(PG8_SB(0, 0), b2);
;       PG8_BAR; PG8_WAIT_L(0); PG8_MMA(0, 1, At, B1); PG8_BAR;
;       PG8_LDA(At, 0, 1); PG8_STAGE(PG8_SA(0, 0), a2);
;       PG8_BAR; PG8_WAIT_L(0); PG8_MMA(1, 0, At, B0); PG8_BAR; PG8_SCHED;
.LBB0_98:
	v_add_u32_e32 v0, s51, v155
	s_add_u32 s6, s35, s4
	ds_read_b128 v[142:145], v0
	ds_read_b128 v[150:153], v0 offset:1024
	ds_read_b128 v[158:161], v0 offset:2048
	ds_read_b128 v[180:183], v0 offset:3072
	s_addc_u32 s7, s36, s5
	s_add_u32 s6, s6, 0x3780100
	s_addc_u32 s7, s7, 0
	s_add_u32 s41, s37, s4
	s_addc_u32 s42, s38, s5
	s_cmpk_eq_i32 s4, 0x700
	s_cselect_b32 s11, s27, s7
	s_cselect_b32 s10, s9, s6
	s_cselect_b32 s7, s34, s42
	s_cselect_b32 s6, s25, s41
	v_lshl_add_u64 v[162:163], v[130:131], 0, s[4:5]
	s_add_i32 m0, s67, 0xc000
	ds_read_b128 v[184:187], v156
	ds_read_b128 v[188:191], v156 offset:1024
	ds_read_b128 v[192:195], v156 offset:2048
	ds_read_b128 v[196:199], v156 offset:3072
	ds_read_b128 v[200:203], v156 offset:4096
	ds_read_b128 v[204:207], v156 offset:5120
	ds_read_b128 v[208:211], v156 offset:6144
	ds_read_b128 v[212:215], v156 offset:7168
	global_load_lds_dwordx4 v[162:163], off
	v_lshl_add_u64 v[162:163], v[132:133], 0, s[4:5]
	s_add_i32 m0, s67, 0xe000
	s_nop 0
	global_load_lds_dwordx4 v[162:163], off
	s_waitcnt lgkmcnt(8)
	s_barrier
	s_waitcnt lgkmcnt(0)
	s_setprio 1
	s_waitcnt lgkmcnt(0)
	v_mfma_f32_16x16x32_bf16 v[126:129], v[142:145], v[184:187], v[126:129]
	v_mfma_f32_16x16x32_bf16 v[122:125], v[158:161], v[184:187], v[122:125]
	v_mfma_f32_16x16x32_bf16 v[118:121], v[142:145], v[192:195], v[118:121]
	v_mfma_f32_16x16x32_bf16 v[114:117], v[158:161], v[192:195], v[114:117]
	v_mfma_f32_16x16x32_bf16 v[110:113], v[142:145], v[200:203], v[110:113]
	v_mfma_f32_16x16x32_bf16 v[106:109], v[158:161], v[200:203], v[106:109]
	v_mfma_f32_16x16x32_bf16 v[102:105], v[142:145], v[208:211], v[102:105]
	v_mfma_f32_16x16x32_bf16 v[98:101], v[158:161], v[208:211], v[98:101]
	v_mfma_f32_16x16x32_bf16 v[126:129], v[150:153], v[188:191], v[126:129]
	v_mfma_f32_16x16x32_bf16 v[122:125], v[180:183], v[188:191], v[122:125]
	v_mfma_f32_16x16x32_bf16 v[118:121], v[150:153], v[196:199], v[118:121]
	v_mfma_f32_16x16x32_bf16 v[114:117], v[180:183], v[196:199], v[114:117]
	v_mfma_f32_16x16x32_bf16 v[110:113], v[150:153], v[204:207], v[110:113]
	v_mfma_f32_16x16x32_bf16 v[106:109], v[180:183], v[204:207], v[106:109]
	v_mfma_f32_16x16x32_bf16 v[102:105], v[150:153], v[212:215], v[102:105]
	v_mfma_f32_16x16x32_bf16 v[98:101], v[180:183], v[212:215], v[98:101]
	s_setprio 0
	s_barrier
	s_mov_b32 m0, s52
	v_add_u32_e32 v0, s71, v155
	v_lshl_add_u64 v[162:163], s[6:7], 0, v[134:135]
	ds_read_b128 v[216:219], v0
	ds_read_b128 v[220:223], v0 offset:1024
	ds_read_b128 v[224:227], v0 offset:2048
	ds_read_b128 v[228:231], v0 offset:3072
	global_load_lds_dwordx4 v[162:163], off
	v_lshl_add_u64 v[232:233], s[6:7], 0, v[136:137]
	s_mov_b32 m0, s62
	s_nop 0
	global_load_lds_dwordx4 v[232:233], off
	s_barrier
	s_waitcnt lgkmcnt(0)
	s_setprio 1
	s_waitcnt lgkmcnt(0)
	v_mfma_f32_16x16x32_bf16 v[62:65], v[216:219], v[184:187], v[62:65]
	v_mfma_f32_16x16x32_bf16 v[58:61], v[224:227], v[184:187], v[58:61]
	v_mfma_f32_16x16x32_bf16 v[54:57], v[216:219], v[192:195], v[54:57]
	v_mfma_f32_16x16x32_bf16 v[50:53], v[224:227], v[192:195], v[50:53]
	v_mfma_f32_16x16x32_bf16 v[46:49], v[216:219], v[200:203], v[46:49]
	v_mfma_f32_16x16x32_bf16 v[42:45], v[224:227], v[200:203], v[42:45]
	v_mfma_f32_16x16x32_bf16 v[38:41], v[216:219], v[208:211], v[38:41]
	v_mfma_f32_16x16x32_bf16 v[34:37], v[224:227], v[208:211], v[34:37]
	v_mfma_f32_16x16x32_bf16 v[62:65], v[220:223], v[188:191], v[62:65]
	v_mfma_f32_16x16x32_bf16 v[58:61], v[228:231], v[188:191], v[58:61]
	v_mfma_f32_16x16x32_bf16 v[54:57], v[220:223], v[196:199], v[54:57]
	v_mfma_f32_16x16x32_bf16 v[50:53], v[228:231], v[196:199], v[50:53]
	v_mfma_f32_16x16x32_bf16 v[46:49], v[220:223], v[204:207], v[46:49]
	v_mfma_f32_16x16x32_bf16 v[42:45], v[228:231], v[204:207], v[42:45]
	v_mfma_f32_16x16x32_bf16 v[38:41], v[220:223], v[212:215], v[38:41]
	v_mfma_f32_16x16x32_bf16 v[34:37], v[228:231], v[212:215], v[34:37]
	s_setprio 0
	s_mov_b32 m0, s67
	v_lshl_add_u64 v[234:235], s[10:11], 0, v[134:135]
	s_barrier
	ds_read_b128 v[184:187], v156 offset:16384
	ds_read_b128 v[188:191], v156 offset:17408
	ds_read_b128 v[192:195], v156 offset:18432
	ds_read_b128 v[196:199], v156 offset:19456
	ds_read_b128 v[200:203], v156 offset:20480
	ds_read_b128 v[204:207], v156 offset:21504
	ds_read_b128 v[208:211], v156 offset:22528
	ds_read_b128 v[212:215], v156 offset:23552
	global_load_lds_dwordx4 v[234:235], off
	v_lshl_add_u64 v[236:237], s[10:11], 0, v[136:137]
	s_mov_b32 m0, s70
	s_nop 0
	global_load_lds_dwordx4 v[236:237], off
	s_barrier
	s_waitcnt lgkmcnt(0)
	s_setprio 1
	s_waitcnt lgkmcnt(0)
	v_mfma_f32_16x16x32_bf16 v[94:97], v[142:145], v[184:187], v[94:97]
	v_mfma_f32_16x16x32_bf16 v[90:93], v[158:161], v[184:187], v[90:93]
	v_mfma_f32_16x16x32_bf16 v[86:89], v[142:145], v[192:195], v[86:89]
	v_mfma_f32_16x16x32_bf16 v[82:85], v[158:161], v[192:195], v[82:85]
	v_mfma_f32_16x16x32_bf16 v[78:81], v[142:145], v[200:203], v[78:81]
	v_mfma_f32_16x16x32_bf16 v[74:77], v[158:161], v[200:203], v[74:77]
	v_mfma_f32_16x16x32_bf16 v[70:73], v[142:145], v[208:211], v[70:73]
	v_mfma_f32_16x16x32_bf16 v[66:69], v[158:161], v[208:211], v[66:69]
	v_mfma_f32_16x16x32_bf16 v[94:97], v[150:153], v[188:191], v[94:97]
	v_mfma_f32_16x16x32_bf16 v[90:93], v[180:183], v[188:191], v[90:93]
	v_mfma_f32_16x16x32_bf16 v[86:89], v[150:153], v[196:199], v[86:89]
	v_mfma_f32_16x16x32_bf16 v[82:85], v[180:183], v[196:199], v[82:85]
	v_mfma_f32_16x16x32_bf16 v[78:81], v[150:153], v[204:207], v[78:81]
	v_mfma_f32_16x16x32_bf16 v[74:77], v[180:183], v[204:207], v[74:77]
	v_mfma_f32_16x16x32_bf16 v[70:73], v[150:153], v[212:215], v[70:73]
	v_mfma_f32_16x16x32_bf16 v[66:69], v[180:183], v[212:215], v[66:69]
	s_setprio 0
	s_barrier
; #define PG8_STAGE(bufoff, gbase) do { _Pragma("unroll") for (int _i = 0; _i < 2; ++_i) \
;     __builtin_amdgcn_global_load_lds((const unsigned*)((const char*)(gbase) + voff[_i]), (LAS unsigned*)(lds + (bufoff) + ldsw + _i * 8192), 16, 0, 0); } while (0)
; #define PG8_LDA(dst, b, h) do { _Pragma("unroll") for (int m = 0; m < 4; ++m) _Pragma("unroll") for (int k = 0; k < 2; ++k) dst[m][k] = *(const LAS bf16x8*)(lds + PG8_SA(b, h) + aoff + m * 2048 + k * 1024); } while (0)
; #define PG8_LDB(dst, b, h) do { _Pragma("unroll") for (int n = 0; n < 2; ++n) _Pragma("unroll") for (int k = 0; k < 2; ++k) dst[n][k] = *(const LAS bf16x8*)(lds + PG8_SB(b, h) + boff + n * 2048 + k * 1024); } while (0)
; #define PG8_MMA(ai, bj, At, Bt_) do { __builtin_amdgcn_s_setprio(1); _Pragma("unroll") for (int m = 0; m < 4; ++m) _Pragma("unroll") for (int n = 0; n < 2; ++n) _Pragma("unroll") for (int k = 0; k < 2; ++k) \
;     acc[ai][bj][m][n] = __builtin_amdgcn_mfma_f32_16x16x32_bf16(Bt_[n][k], At[m][k], acc[ai][bj][m][n], 0, 0, 0); __builtin_amdgcn_s_setprio(0); } while (0)
; #define PG8_WAIT_V(n) asm volatile("s_waitcnt vmcnt(" #n ")" ::: "memory")
; #define PG8_WAIT_L(n) asm volatile("s_waitcnt lgkmcnt(" #n ")" ::: "memory")
; #define PG8_BAR __builtin_amdgcn_s_barrier()
; #define PG8_SCHED __builtin_amdgcn_sched_barrier(0)
; template <int EPI>
; __device__ __forceinline__ void gemm_phase(KP P, const bfu* __restrict__ A, const bfu* __restrict__ Bt, int K, int ntn, char* smem, const int wv) {
;     ...
;       PG8_STAGE(PG8_SB(0, 1), b2 + hstep);
;       PG8_WAIT_V(6); PG8_BAR; PG8_MMA(1, 1, At, B1); PG8_BAR;
;       PG8_LDB(B0, 1, 0); PG8_SCHED; PG8_LDA(At, 1, 0); PG8_STAGE(PG8_SA(0, 1), a2 + hstep);
;       PG8_WAIT_L(8); PG8_BAR; PG8_WAIT_L(0); PG8_MMA(0, 0, At, B0); PG8_BAR; PG8_SCHED;
;       PG8_LDB(B1, 1, 1); PG8_STAGE(PG8_SB(1, 0), b3);
;       PG8_BAR; PG8_WAIT_L(0); PG8_MMA(0, 1, At, B1); PG8_BAR;
;       PG8_LDA(At, 1, 1); PG8_STAGE(PG8_SA(1, 0), a3);
	s_add_u32 s42, s6, 0x40000
	s_addc_u32 s43, s7, 0
	s_mov_b32 m0, s74
	v_lshl_add_u64 v[142:143], s[42:43], 0, v[134:135]
	global_load_lds_dwordx4 v[142:143], off
	v_lshl_add_u64 v[142:143], s[42:43], 0, v[136:137]
	s_mov_b32 m0, s75
	s_nop 0
	global_load_lds_dwordx4 v[142:143], off
	s_waitcnt vmcnt(6)
	s_barrier
	s_setprio 1
	v_mfma_f32_16x16x32_bf16 v[30:33], v[216:219], v[184:187], v[30:33]
	v_mfma_f32_16x16x32_bf16 v[26:29], v[224:227], v[184:187], v[26:29]
	v_mfma_f32_16x16x32_bf16 v[22:25], v[216:219], v[192:195], v[22:25]
	v_mfma_f32_16x16x32_bf16 v[18:21], v[224:227], v[192:195], v[18:21]
	v_mfma_f32_16x16x32_bf16 v[14:17], v[216:219], v[200:203], v[14:17]
	v_mfma_f32_16x16x32_bf16 v[10:13], v[224:227], v[200:203], v[10:13]
	v_mfma_f32_16x16x32_bf16 v[6:9], v[216:219], v[208:211], v[6:9]
	v_mfma_f32_16x16x32_bf16 v[2:5], v[224:227], v[208:211], v[2:5]
	v_mfma_f32_16x16x32_bf16 v[30:33], v[220:223], v[188:191], v[30:33]
	v_mfma_f32_16x16x32_bf16 v[26:29], v[228:231], v[188:191], v[26:29]
	v_mfma_f32_16x16x32_bf16 v[22:25], v[220:223], v[196:199], v[22:25]
	v_mfma_f32_16x16x32_bf16 v[18:21], v[228:231], v[196:199], v[18:21]
	v_mfma_f32_16x16x32_bf16 v[14:17], v[220:223], v[204:207], v[14:17]
	v_mfma_f32_16x16x32_bf16 v[10:13], v[228:231], v[204:207], v[10:13]
	v_mfma_f32_16x16x32_bf16 v[6:9], v[220:223], v[212:215], v[6:9]
	v_mfma_f32_16x16x32_bf16 v[2:5], v[228:231], v[212:215], v[2:5]
	s_setprio 0
	v_add_u32_e32 v0, s78, v155
	s_barrier
	ds_read_b128 v[142:145], v0
	ds_read_b128 v[150:153], v0 offset:1024
	ds_read_b128 v[158:161], v0 offset:2048
	ds_read_b128 v[180:183], v0 offset:3072
	s_add_u32 s10, s10, 0x40000
	s_addc_u32 s11, s11, 0
	s_mov_b32 m0, s76
	v_lshl_add_u64 v[216:217], s[10:11], 0, v[134:135]
	ds_read_b128 v[184:187], v156 offset:32768
	ds_read_b128 v[188:191], v156 offset:33792
	ds_read_b128 v[192:195], v156 offset:34816
	ds_read_b128 v[196:199], v156 offset:35840
	ds_read_b128 v[200:203], v156 offset:36864
	ds_read_b128 v[204:207], v156 offset:37888
	ds_read_b128 v[208:211], v156 offset:38912
	ds_read_b128 v[212:215], v156 offset:39936
	global_load_lds_dwordx4 v[216:217], off
	v_lshl_add_u64 v[216:217], s[10:11], 0, v[136:137]
	s_mov_b32 m0, s77
	s_nop 0
	global_load_lds_dwordx4 v[216:217], off
	s_waitcnt lgkmcnt(8)
	s_barrier
	s_waitcnt lgkmcnt(0)
	s_setprio 1
	s_waitcnt lgkmcnt(0)
	v_mfma_f32_16x16x32_bf16 v[126:129], v[142:145], v[184:187], v[126:129]
	v_mfma_f32_16x16x32_bf16 v[122:125], v[158:161], v[184:187], v[122:125]
	v_mfma_f32_16x16x32_bf16 v[118:121], v[142:145], v[192:195], v[118:121]
	v_mfma_f32_16x16x32_bf16 v[114:117], v[158:161], v[192:195], v[114:117]
	v_mfma_f32_16x16x32_bf16 v[110:113], v[142:145], v[200:203], v[110:113]
	v_mfma_f32_16x16x32_bf16 v[106:109], v[158:161], v[200:203], v[106:109]
	v_mfma_f32_16x16x32_bf16 v[102:105], v[142:145], v[208:211], v[102:105]
	v_mfma_f32_16x16x32_bf16 v[98:101], v[158:161], v[208:211], v[98:101]
	v_mfma_f32_16x16x32_bf16 v[126:129], v[150:153], v[188:191], v[126:129]
	v_mfma_f32_16x16x32_bf16 v[122:125], v[180:183], v[188:191], v[122:125]
	v_mfma_f32_16x16x32_bf16 v[118:121], v[150:153], v[196:199], v[118:121]
	v_mfma_f32_16x16x32_bf16 v[114:117], v[180:183], v[196:199], v[114:117]
	v_mfma_f32_16x16x32_bf16 v[110:113], v[150:153], v[204:207], v[110:113]
	v_mfma_f32_16x16x32_bf16 v[106:109], v[180:183], v[204:207], v[106:109]
	v_mfma_f32_16x16x32_bf16 v[102:105], v[150:153], v[212:215], v[102:105]
	v_mfma_f32_16x16x32_bf16 v[98:101], v[180:183], v[212:215], v[98:101]
	s_setprio 0
	s_barrier
	s_mov_b32 m0, s79
	v_add_u32_e32 v0, s83, v155
	v_lshl_add_u64 v[162:163], v[162:163], 0, s[90:91]
	ds_read_b128 v[216:219], v0
	ds_read_b128 v[220:223], v0 offset:1024
	ds_read_b128 v[224:227], v0 offset:2048
	ds_read_b128 v[228:231], v0 offset:3072
	global_load_lds_dwordx4 v[162:163], off
	v_lshl_add_u64 v[162:163], v[232:233], 0, s[90:91]
	s_mov_b32 m0, s80
	s_nop 0
	global_load_lds_dwordx4 v[162:163], off
	s_barrier
	s_waitcnt lgkmcnt(0)
	s_setprio 1
	s_waitcnt lgkmcnt(0)
	v_mfma_f32_16x16x32_bf16 v[62:65], v[216:219], v[184:187], v[62:65]
	v_mfma_f32_16x16x32_bf16 v[58:61], v[224:227], v[184:187], v[58:61]
	v_mfma_f32_16x16x32_bf16 v[54:57], v[216:219], v[192:195], v[54:57]
	v_mfma_f32_16x16x32_bf16 v[50:53], v[224:227], v[192:195], v[50:53]
	v_mfma_f32_16x16x32_bf16 v[46:49], v[216:219], v[200:203], v[46:49]
	v_mfma_f32_16x16x32_bf16 v[42:45], v[224:227], v[200:203], v[42:45]
	v_mfma_f32_16x16x32_bf16 v[38:41], v[216:219], v[208:211], v[38:41]
	v_mfma_f32_16x16x32_bf16 v[34:37], v[224:227], v[208:211], v[34:37]
	v_mfma_f32_16x16x32_bf16 v[62:65], v[220:223], v[188:191], v[62:65]
	v_mfma_f32_16x16x32_bf16 v[58:61], v[228:231], v[188:191], v[58:61]
	v_mfma_f32_16x16x32_bf16 v[54:57], v[220:223], v[196:199], v[54:57]
	v_mfma_f32_16x16x32_bf16 v[50:53], v[228:231], v[196:199], v[50:53]
	v_mfma_f32_16x16x32_bf16 v[46:49], v[220:223], v[204:207], v[46:49]
	v_mfma_f32_16x16x32_bf16 v[42:45], v[228:231], v[204:207], v[42:45]
	v_mfma_f32_16x16x32_bf16 v[38:41], v[220:223], v[212:215], v[38:41]
	v_mfma_f32_16x16x32_bf16 v[34:37], v[228:231], v[212:215], v[34:37]
	s_setprio 0
	s_mov_b32 m0, s81
	v_lshl_add_u64 v[162:163], v[234:235], 0, s[90:91]
	s_barrier
; #define PG8_STAGE(bufoff, gbase) do { _Pragma("unroll") for (int _i = 0; _i < 2; ++_i) \
;     __builtin_amdgcn_global_load_lds((const unsigned*)((const char*)(gbase) + voff[_i]), (LAS unsigned*)(lds + (bufoff) + ldsw + _i * 8192), 16, 0, 0); } while (0)
; #define PG8_MMA(ai, bj, At, Bt_) do { __builtin_amdgcn_s_setprio(1); _Pragma("unroll") for (int m = 0; m < 4; ++m) _Pragma("unroll") for (int n = 0; n < 2; ++n) _Pragma("unroll") for (int k = 0; k < 2; ++k) \
;     acc[ai][bj][m][n] = __builtin_amdgcn_mfma_f32_16x16x32_bf16(Bt_[n][k], At[m][k], acc[ai][bj][m][n], 0, 0, 0); __builtin_amdgcn_s_setprio(0); } while (0)
; #define PG8_WAIT_V(n) asm volatile("s_waitcnt vmcnt(" #n ")" ::: "memory")
; #define PG8_WAIT_L(n) asm volatile("s_waitcnt lgkmcnt(" #n ")" ::: "memory")
; #define PG8_BAR __builtin_amdgcn_s_barrier()
; #define PG8_SCHED __builtin_amdgcn_sched_barrier(0)
; template <int EPI>
; __device__ __forceinline__ void gemm_epilogue(KP P, f32x4 (&acc)[2][2][4][2], int brow, int bcol, int wr, int wc, int fr_, int fq_, const float* sRu) {
;     ...
;       float* fdst = prompt ? P->out + O_VP + (size_t)brow * 1024 + (bcol - 2048) : P->out + O_VS + (size_t)(brow - MP) * 1024 + (bcol - 2048);
;       bfu* vt = prompt ? (bfu*)(P->ws + WS_VTP) : (bfu*)(P->ws + WS_VTS);
; #pragma unroll
;       for (int ai = 0; ai < 2; ++ai)
; #pragma unroll
;         for (int m = 0; m < 4; ++m) {
;           __builtin_amdgcn_sched_barrier(0);
;           unsigned lr = lrow0 + ai * 128 + m * 16;
;           int row = brow + lr;
;           size_t tb;
;           unsigned tstr;
;           if (prompt) { tb = (size_t)(row >> 12) * 1024 * 4096 + (row & 4095); tstr = 4096; }
;           else { int rs = row - MP; tb = (size_t)(rs >> 6) * 1024 * SKV + 1024 + (rs & 63); tstr = SKV; }
; template <int EPI>
; __device__ __forceinline__ void gemm_phase(KP P, const bfu* __restrict__ A, const bfu* __restrict__ Bt, int K, int ntn, char* smem, const int wv) {
;     ...
;       PG8_BAR; PG8_WAIT_L(0); PG8_MMA(1, 0, At, B0); PG8_BAR; PG8_SCHED;
;       PG8_STAGE(PG8_SB(1, 1), b3 + hstep);
;       PG8_WAIT_V(6); PG8_BAR; PG8_MMA(1, 1, At, B1); PG8_BAR;
;     }
	ds_read_b128 v[184:187], v156 offset:49152
	ds_read_b128 v[188:191], v156 offset:50176
	ds_read_b128 v[192:195], v156 offset:51200
	ds_read_b128 v[196:199], v156 offset:52224
	ds_read_b128 v[200:203], v156 offset:53248
	ds_read_b128 v[204:207], v156 offset:54272
	ds_read_b128 v[208:211], v156 offset:55296
	ds_read_b128 v[212:215], v156 offset:56320
	global_load_lds_dwordx4 v[162:163], off
	v_lshl_add_u64 v[162:163], v[236:237], 0, s[90:91]
	s_mov_b32 m0, s82
	s_nop 0
	global_load_lds_dwordx4 v[162:163], off
	s_barrier
	s_waitcnt lgkmcnt(0)
	s_setprio 1
	s_waitcnt lgkmcnt(0)
	v_mfma_f32_16x16x32_bf16 v[94:97], v[142:145], v[184:187], v[94:97]
	v_mfma_f32_16x16x32_bf16 v[90:93], v[158:161], v[184:187], v[90:93]
	v_mfma_f32_16x16x32_bf16 v[86:89], v[142:145], v[192:195], v[86:89]
	v_mfma_f32_16x16x32_bf16 v[82:85], v[158:161], v[192:195], v[82:85]
	v_mfma_f32_16x16x32_bf16 v[78:81], v[142:145], v[200:203], v[78:81]
	v_mfma_f32_16x16x32_bf16 v[74:77], v[158:161], v[200:203], v[74:77]
	v_mfma_f32_16x16x32_bf16 v[70:73], v[142:145], v[208:211], v[70:73]
	v_mfma_f32_16x16x32_bf16 v[66:69], v[158:161], v[208:211], v[66:69]
	v_mfma_f32_16x16x32_bf16 v[94:97], v[150:153], v[188:191], v[94:97]
	v_mfma_f32_16x16x32_bf16 v[90:93], v[180:183], v[188:191], v[90:93]
	v_mfma_f32_16x16x32_bf16 v[86:89], v[150:153], v[196:199], v[86:89]
	v_mfma_f32_16x16x32_bf16 v[82:85], v[180:183], v[196:199], v[82:85]
	v_mfma_f32_16x16x32_bf16 v[78:81], v[150:153], v[204:207], v[78:81]
	v_mfma_f32_16x16x32_bf16 v[74:77], v[180:183], v[204:207], v[74:77]
	v_mfma_f32_16x16x32_bf16 v[70:73], v[150:153], v[212:215], v[70:73]
	v_mfma_f32_16x16x32_bf16 v[66:69], v[180:183], v[212:215], v[66:69]
	s_setprio 0
	s_barrier
	s_add_u32 s6, s6, 0x40080
	s_addc_u32 s7, s7, 0
	s_mov_b32 m0, s84
	v_lshl_add_u64 v[142:143], s[6:7], 0, v[134:135]
	global_load_lds_dwordx4 v[142:143], off
	v_lshl_add_u64 v[142:143], s[6:7], 0, v[136:137]
	s_mov_b32 m0, s86
	s_nop 0
	global_load_lds_dwordx4 v[142:143], off
	s_waitcnt vmcnt(6)
	s_barrier
	s_setprio 1
	v_mfma_f32_16x16x32_bf16 v[30:33], v[216:219], v[184:187], v[30:33]
	v_mfma_f32_16x16x32_bf16 v[26:29], v[224:227], v[184:187], v[26:29]
	v_mfma_f32_16x16x32_bf16 v[22:25], v[216:219], v[192:195], v[22:25]
	v_mfma_f32_16x16x32_bf16 v[18:21], v[224:227], v[192:195], v[18:21]
	v_mfma_f32_16x16x32_bf16 v[14:17], v[216:219], v[200:203], v[14:17]
	v_mfma_f32_16x16x32_bf16 v[10:13], v[224:227], v[200:203], v[10:13]
	v_mfma_f32_16x16x32_bf16 v[6:9], v[216:219], v[208:211], v[6:9]
	v_mfma_f32_16x16x32_bf16 v[2:5], v[224:227], v[208:211], v[2:5]
	v_mfma_f32_16x16x32_bf16 v[30:33], v[220:223], v[188:191], v[30:33]
	v_mfma_f32_16x16x32_bf16 v[26:29], v[228:231], v[188:191], v[26:29]
	v_mfma_f32_16x16x32_bf16 v[22:25], v[220:223], v[196:199], v[22:25]
	v_mfma_f32_16x16x32_bf16 v[18:21], v[228:231], v[196:199], v[18:21]
	v_mfma_f32_16x16x32_bf16 v[14:17], v[220:223], v[204:207], v[14:17]
	v_mfma_f32_16x16x32_bf16 v[10:13], v[228:231], v[204:207], v[10:13]
	v_mfma_f32_16x16x32_bf16 v[6:9], v[220:223], v[212:215], v[6:9]
	v_mfma_f32_16x16x32_bf16 v[2:5], v[228:231], v[212:215], v[2:5]
	s_setprio 0
	s_add_i32 s39, s39, 2
	s_add_u32 s4, s4, 0x100
	s_addc_u32 s5, s5, 0
	s_cmp_gt_u32 s39, 13
	s_barrier
	s_cbranch_scc0 .LBB0_98
	s_lshl_b32 s4, s8, 8
	s_lshl_b32 s42, s40, 8
	s_cmpk_lt_i32 s8, 0x100
	s_cselect_b64 s[6:7], -1, 0
	s_cmpk_gt_i32 s8, 0xff
	s_cselect_b64 s[10:11], -1, 0
	s_add_i32 s60, s4, 0xffff0000
	v_mov_b32_e32 v157, v149
	v_mov_b32_e32 v158, v154
	s_cmp_gt_i32 s40, 7
	s_mov_b64 s[8:9], -1
	s_cbranch_scc0 .LBB0_133
	v_mbcnt_lo_u32_b32 v196, -1, 0
	v_mbcnt_hi_u32_b32 v196, -1, v196
	v_and_b32_e32 v196, 3, v196
	v_mov_b32_e32 v197, 0x7060302
	v_mov_b32_e32 v198, 0x7060504
	v_mov_b32_e32 v199, 0x3020100
	v_cmp_gt_u32_e32 vcc, 2, v196
	v_mov_b32_e32 v200, 0x3020100
	v_mov_b32_e32 v201, 0x5040100
	s_nop 1
	v_cndmask_b32_e32 v198, v200, v198, vcc
	v_mov_b32_e32 v200, 0x7060504
	v_cndmask_b32_e32 v199, v200, v199, vcc
	v_and_b32_e32 v200, 1, v196
	v_cmp_eq_u32_e32 vcc, 0, v200
	v_mov_b32_e32 v200, 0x3020706
	s_nop 1
	v_cndmask_b32_e32 v201, v200, v201, vcc
	v_lshlrev_b32_e32 v202, 1, v196
	v_sub_u32_e32 v202, 0, v202
	v_ashrrev_i32_e32 v203, 31, v202
	v_add_u32_e32 v150, s94, v157
	v_and_b32_e32 v190, 63, v157
	v_add_u32_e32 v0, s4, v150
	s_and_b64 vcc, exec, s[10:11]
	s_cbranch_vccz .LBB0_102
	v_add_u32_e32 v130, 0xffff0000, v0
	v_ashrrev_i32_e32 v130, 6, v130
	s_mov_b32 s5, 0x110000
	v_mad_i64_i32 v[130:131], s[8:9], v130, s5, 0
	s_movk_i32 s5, 0x400
	v_or3_b32 v130, v130, v190, s5
	s_mov_b64 s[8:9], 0

; template <int EPI>
; __device__ __forceinline__ void gemm_epilogue(KP P, f32x4 (&acc)[2][2][4][2], int brow, int bcol, int wr, int wc, int fr_, int fq_, const float* sRu) {
;     ...
;       for (int ai = 0; ai < 2; ++ai)
; #pragma unroll
;         for (int m = 0; m < 4; ++m) {
;           __builtin_amdgcn_sched_barrier(0);
;           unsigned lr = lrow0 + ai * 128 + m * 16;
;           int row = brow + lr;
;           size_t tb;
;           unsigned tstr;
;           if (prompt) { tb = (size_t)(row >> 12) * 1024 * 4096 + (row & 4095); tstr = 4096; }
;           else { int rs = row - MP; tb = (size_t)(rs >> 6) * 1024 * SKV + 1024 + (rs & 63); tstr = SKV; }
; #pragma unroll
;           for (int bj = 0; bj < 2; ++bj)
; #pragma unroll
;             for (int n = 0; n < 2; ++n) {
;               f32x4 v = acc[ai][bj][m][n];
;               unsigned lc = lcol0 + bj * 128 + n * 16;
;               *(f32x4*)(fdst + lr * 1024 + lc) = v;
;               unsigned c = bcol - 2048 + lc;
; #pragma unroll
;               for (int j = 0; j < 4; ++j) vt[tb + (size_t)(c + j) * tstr] = f2bf(v[j]);
;             }
;         }
.LBB0_104:
	s_ashr_i32 s5, s4, 31
	s_and_b64 s[36:37], s[6:7], exec
	s_cselect_b32 s37, s5, 0
	s_cselect_b32 s36, s4, s60
	s_mov_b32 s5, 0x2128e000
	s_cselect_b32 s5, s5, 0x31cd6000
	s_lshl_b64 s[36:37], s[36:37], 12
	s_waitcnt lgkmcnt(0)
	s_add_u32 s9, s34, s36
	s_mov_b32 s43, s61
	s_addc_u32 s25, s35, s37
	s_lshl_b64 s[34:35], s[42:43], 2
	s_add_u32 s9, s9, s34
	s_addc_u32 s25, s25, s35
	s_add_u32 s34, s9, s5
	s_addc_u32 s35, s25, 0
	s_and_b64 s[36:37], s[6:7], exec
	s_mov_b32 s5, 0x1c598000
	s_cselect_b32 s5, s5, 0x25698000
	v_add_u32_e32 v0, 16, v157
	v_readlane_b32 s9, v241, 17
	s_add_u32 s36, s18, s5
	v_and_b32_e32 v187, 63, v0
	v_lshl_add_u32 v183, v158, 2, s9
	v_lshlrev_b32_e32 v0, 10, v150
	s_addc_u32 s37, s19, 0
	v_lshl_add_u64 v[144:145], v[0:1], 2, s[34:35]
	v_mov_b32_e32 v0, v183
	s_add_i32 s5, s42, 0xfffff800
	v_lshl_add_u64 v[188:189], v[130:131], 1, s[36:37]
	v_lshl_add_u64 v[130:131], v[0:1], 2, v[144:145]
	global_store_dwordx4 v[130:131], v[126:129], off
	v_add_u32_e32 v151, s5, v183
	v_add_u32_e32 v130, 16, v183
	v_mov_b32_e32 v131, v1
	v_lshl_add_u64 v[132:133], v[130:131], 2, v[144:145]
	global_store_dwordx4 v[132:133], v[122:125], off
	v_add_u32_e32 v160, s5, v130
	v_lshl_add_u64 v[222:223], v[188:189], 0, v[202:203]
	v_add_u32_e32 v204, v151, v196
	v_add_u32_e32 v205, v160, v196
	v_bfe_u32 v208, v126, 16, 1
	v_bfe_u32 v224, v122, 16, 1
	v_bfe_u32 v209, v127, 16, 1
	v_bfe_u32 v225, v123, 16, 1
	v_bfe_u32 v210, v128, 16, 1
	v_bfe_u32 v226, v124, 16, 1
	v_bfe_u32 v211, v129, 16, 1
	v_bfe_u32 v227, v125, 16, 1
	v_add3_u32 v208, v126, v208, s96
	v_add3_u32 v224, v122, v224, s96
	v_add3_u32 v209, v127, v209, s96
	v_add3_u32 v225, v123, v225, s96
	v_add3_u32 v210, v128, v210, s96
	v_add3_u32 v226, v124, v226, s96
	v_add3_u32 v211, v129, v211, s96
	v_add3_u32 v227, v125, v227, s96
	v_perm_b32 v212, v209, v208, v197
	v_perm_b32 v228, v225, v224, v197
	v_perm_b32 v213, v211, v210, v197
	v_perm_b32 v229, v227, v226, v197
	v_perm_b32 v214, v213, v212, v198
	v_perm_b32 v230, v229, v228, v198
	v_mad_u64_u32 v[208:209], s[38:39], s8, v204, 0
	v_mad_u64_u32 v[224:225], s[38:39], s8, v205, 0
	s_nop 0
	v_mov_b32_dpp v215, v214 quad_perm:[2,3,0,1] row_mask:0xf bank_mask:0xf
	v_mov_b32_dpp v231, v230 quad_perm:[2,3,0,1] row_mask:0xf bank_mask:0xf
	v_perm_b32 v216, v215, v212, v199
	v_perm_b32 v232, v231, v228, v199
	v_perm_b32 v217, v215, v213, v198
	v_perm_b32 v233, v231, v229, v198
	v_lshl_add_u64 v[208:209], v[208:209], 1, v[222:223]
	v_lshl_add_u64 v[224:225], v[224:225], 1, v[222:223]
	v_mov_b32_dpp v218, v216 quad_perm:[1,0,3,2] row_mask:0xf bank_mask:0xf
	v_mov_b32_dpp v234, v232 quad_perm:[1,0,3,2] row_mask:0xf bank_mask:0xf
	v_mov_b32_dpp v219, v217 quad_perm:[1,0,3,2] row_mask:0xf bank_mask:0xf
	v_mov_b32_dpp v235, v233 quad_perm:[1,0,3,2] row_mask:0xf bank_mask:0xf
	v_perm_b32 v220, v218, v216, v201
	v_perm_b32 v236, v234, v232, v201
	v_perm_b32 v221, v219, v217, v201
	v_perm_b32 v237, v235, v233, v201
	global_store_dwordx2 v[208:209], v[220:221], off
	global_store_dwordx2 v[224:225], v[236:237], off
	v_add_u32_e32 v132, 0x80, v183
	v_mov_b32_e32 v133, v1
	v_lshl_add_u64 v[142:143], v[132:133], 2, v[144:145]
	global_store_dwordx4 v[142:143], v[62:65], off
	v_add_u32_e32 v179, s5, v132
	v_add_u32_e32 v142, 0x90, v183
	v_mov_b32_e32 v143, v1
	v_lshl_add_u64 v[144:145], v[142:143], 2, v[144:145]
	global_store_dwordx4 v[144:145], v[58:61], off
	v_add_u32_e32 v183, s5, v142
	v_add_u32_e32 v206, v179, v196
	v_add_u32_e32 v207, v183, v196
	v_bfe_u32 v208, v62, 16, 1
	v_bfe_u32 v224, v58, 16, 1
	v_bfe_u32 v209, v63, 16, 1
	v_bfe_u32 v225, v59, 16, 1
	v_bfe_u32 v210, v64, 16, 1
	v_bfe_u32 v226, v60, 16, 1
	v_bfe_u32 v211, v65, 16, 1
	v_bfe_u32 v227, v61, 16, 1
	v_add3_u32 v208, v62, v208, s96
	v_add3_u32 v224, v58, v224, s96
	v_add3_u32 v209, v63, v209, s96
	v_add3_u32 v225, v59, v225, s96
	v_add3_u32 v210, v64, v210, s96
	v_add3_u32 v226, v60, v226, s96
	v_add3_u32 v211, v65, v211, s96
	v_add3_u32 v227, v61, v227, s96
	v_perm_b32 v212, v209, v208, v197
	v_perm_b32 v228, v225, v224, v197
	v_perm_b32 v213, v211, v210, v197
	v_perm_b32 v229, v227, v226, v197
	v_perm_b32 v214, v213, v212, v198
	v_perm_b32 v230, v229, v228, v198
	v_mad_u64_u32 v[208:209], s[38:39], s8, v206, 0
	v_mad_u64_u32 v[224:225], s[38:39], s8, v207, 0
	s_nop 0
	v_mov_b32_dpp v215, v214 quad_perm:[2,3,0,1] row_mask:0xf bank_mask:0xf
	v_mov_b32_dpp v231, v230 quad_perm:[2,3,0,1] row_mask:0xf bank_mask:0xf
	v_perm_b32 v216, v215, v212, v199
	v_perm_b32 v232, v231, v228, v199
	v_perm_b32 v217, v215, v213, v198
	v_perm_b32 v233, v231, v229, v198
	v_lshl_add_u64 v[208:209], v[208:209], 1, v[222:223]
	v_lshl_add_u64 v[224:225], v[224:225], 1, v[222:223]
	v_mov_b32_dpp v218, v216 quad_perm:[1,0,3,2] row_mask:0xf bank_mask:0xf
	v_mov_b32_dpp v234, v232 quad_perm:[1,0,3,2] row_mask:0xf bank_mask:0xf
	v_mov_b32_dpp v219, v217 quad_perm:[1,0,3,2] row_mask:0xf bank_mask:0xf
	v_mov_b32_dpp v235, v233 quad_perm:[1,0,3,2] row_mask:0xf bank_mask:0xf
	v_perm_b32 v220, v218, v216, v201
	v_perm_b32 v236, v234, v232, v201
	v_perm_b32 v221, v219, v217, v201
	v_perm_b32 v237, v235, v233, v201
	global_store_dwordx2 v[208:209], v[220:221], off
	global_store_dwordx2 v[224:225], v[236:237], off
	v_add_u32_e32 v189, 16, v150
	v_cndmask_b32_e64 v144, 0, 1, s[10:11]
	v_add_u32_e32 v188, s4, v189
	v_cmp_ne_u32_e64 s[8:9], 1, v144
	s_andn2_b64 vcc, exec, s[10:11]
	s_mov_b64 s[38:39], -1
	s_cbranch_vccnz .LBB0_106
	v_add_u32_e32 v144, 0xffff0000, v188
	v_ashrrev_i32_e32 v144, 6, v144
	s_mov_b32 s5, 0x110000
	v_mad_i64_i32 v[144:145], s[38:39], v144, s5, 0
	s_movk_i32 s5, 0x400
	v_or3_b32 v144, v144, v187, s5
	s_mov_b64 s[38:39], 0

; template <int EPI>
; __device__ __forceinline__ void gemm_epilogue(KP P, f32x4 (&acc)[2][2][4][2], int brow, int bcol, int wr, int wc, int fr_, int fq_, const float* sRu) {
;     ...
;       for (int ai = 0; ai < 2; ++ai)
; #pragma unroll
;         for (int m = 0; m < 4; ++m) {
;           __builtin_amdgcn_sched_barrier(0);
;           unsigned lr = lrow0 + ai * 128 + m * 16;
;           int row = brow + lr;
;           size_t tb;
;           unsigned tstr;
;           if (prompt) { tb = (size_t)(row >> 12) * 1024 * 4096 + (row & 4095); tstr = 4096; }
;           else { int rs = row - MP; tb = (size_t)(rs >> 6) * 1024 * SKV + 1024 + (rs & 63); tstr = SKV; }
; #pragma unroll
;           for (int bj = 0; bj < 2; ++bj)
; #pragma unroll
;             for (int n = 0; n < 2; ++n) {
;               f32x4 v = acc[ai][bj][m][n];
;               unsigned lc = lcol0 + bj * 128 + n * 16;
;               *(f32x4*)(fdst + lr * 1024 + lc) = v;
;               unsigned c = bcol - 2048 + lc;
; #pragma unroll
;               for (int j = 0; j < 4; ++j) vt[tb + (size_t)(c + j) * tstr] = f2bf(v[j]);
;             }
;         }
.LBB0_108:
	v_lshlrev_b32_e32 v192, 10, v189
	v_mov_b32_e32 v193, v1
	v_lshl_add_u64 v[192:193], v[192:193], 2, s[34:35]
	v_lshl_add_u64 v[194:195], v[0:1], 2, v[192:193]
	v_lshl_add_u64 v[144:145], v[144:145], 1, s[36:37]
	global_store_dwordx4 v[194:195], v[118:121], off
	v_lshl_add_u64 v[194:195], v[130:131], 2, v[192:193]
	global_store_dwordx4 v[194:195], v[114:117], off
	v_lshl_add_u64 v[222:223], v[144:145], 0, v[202:203]
	v_bfe_u32 v208, v118, 16, 1
	v_bfe_u32 v224, v114, 16, 1
	v_bfe_u32 v209, v119, 16, 1
	v_bfe_u32 v225, v115, 16, 1
	v_bfe_u32 v210, v120, 16, 1
	v_bfe_u32 v226, v116, 16, 1
	v_bfe_u32 v211, v121, 16, 1
	v_bfe_u32 v227, v117, 16, 1
	v_add3_u32 v208, v118, v208, s96
	v_add3_u32 v224, v114, v224, s96
	v_add3_u32 v209, v119, v209, s96
	v_add3_u32 v225, v115, v225, s96
	v_add3_u32 v210, v120, v210, s96
	v_add3_u32 v226, v116, v226, s96
	v_add3_u32 v211, v121, v211, s96
	v_add3_u32 v227, v117, v227, s96
	v_perm_b32 v212, v209, v208, v197
	v_perm_b32 v228, v225, v224, v197
	v_perm_b32 v213, v211, v210, v197
	v_perm_b32 v229, v227, v226, v197
	v_perm_b32 v214, v213, v212, v198
	v_perm_b32 v230, v229, v228, v198
	v_mad_u64_u32 v[208:209], s[44:45], s38, v204, 0
	v_mad_u64_u32 v[224:225], s[44:45], s38, v205, 0
	s_nop 0
	v_mov_b32_dpp v215, v214 quad_perm:[2,3,0,1] row_mask:0xf bank_mask:0xf
	v_mov_b32_dpp v231, v230 quad_perm:[2,3,0,1] row_mask:0xf bank_mask:0xf
	v_perm_b32 v216, v215, v212, v199
	v_perm_b32 v232, v231, v228, v199
	v_perm_b32 v217, v215, v213, v198
	v_perm_b32 v233, v231, v229, v198
	v_lshl_add_u64 v[208:209], v[208:209], 1, v[222:223]
	v_lshl_add_u64 v[224:225], v[224:225], 1, v[222:223]
	v_mov_b32_dpp v218, v216 quad_perm:[1,0,3,2] row_mask:0xf bank_mask:0xf
	v_mov_b32_dpp v234, v232 quad_perm:[1,0,3,2] row_mask:0xf bank_mask:0xf
	v_mov_b32_dpp v219, v217 quad_perm:[1,0,3,2] row_mask:0xf bank_mask:0xf
	v_mov_b32_dpp v235, v233 quad_perm:[1,0,3,2] row_mask:0xf bank_mask:0xf
	v_perm_b32 v220, v218, v216, v201
	v_perm_b32 v236, v234, v232, v201
	v_perm_b32 v221, v219, v217, v201
	v_perm_b32 v237, v235, v233, v201
	global_store_dwordx2 v[208:209], v[220:221], off
	global_store_dwordx2 v[224:225], v[236:237], off
	v_lshl_add_u64 v[194:195], v[132:133], 2, v[192:193]
	global_store_dwordx4 v[194:195], v[54:57], off
	v_lshl_add_u64 v[192:193], v[142:143], 2, v[192:193]
	global_store_dwordx4 v[192:193], v[50:53], off
	v_xor_b32_e32 v188, 32, v190
	v_bfe_u32 v208, v54, 16, 1
	v_bfe_u32 v224, v50, 16, 1
	v_bfe_u32 v209, v55, 16, 1
	v_bfe_u32 v225, v51, 16, 1
	v_bfe_u32 v210, v56, 16, 1
	v_bfe_u32 v226, v52, 16, 1
	v_bfe_u32 v211, v57, 16, 1
	v_bfe_u32 v227, v53, 16, 1
	v_add3_u32 v208, v54, v208, s96
	v_add3_u32 v224, v50, v224, s96
	v_add3_u32 v209, v55, v209, s96
	v_add3_u32 v225, v51, v225, s96
	v_add3_u32 v210, v56, v210, s96
	v_add3_u32 v226, v52, v226, s96
	v_add3_u32 v211, v57, v211, s96
	v_add3_u32 v227, v53, v227, s96
	v_perm_b32 v212, v209, v208, v197
	v_perm_b32 v228, v225, v224, v197
	v_perm_b32 v213, v211, v210, v197
	v_perm_b32 v229, v227, v226, v197
	v_perm_b32 v214, v213, v212, v198
	v_perm_b32 v230, v229, v228, v198
	v_mad_u64_u32 v[208:209], s[44:45], s38, v206, 0
	v_mad_u64_u32 v[224:225], s[44:45], s38, v207, 0
	s_nop 0
	v_mov_b32_dpp v215, v214 quad_perm:[2,3,0,1] row_mask:0xf bank_mask:0xf
	v_mov_b32_dpp v231, v230 quad_perm:[2,3,0,1] row_mask:0xf bank_mask:0xf
	v_perm_b32 v216, v215, v212, v199
	v_perm_b32 v232, v231, v228, v199
	v_perm_b32 v217, v215, v213, v198
	v_perm_b32 v233, v231, v229, v198
	v_lshl_add_u64 v[208:209], v[208:209], 1, v[222:223]
	v_lshl_add_u64 v[224:225], v[224:225], 1, v[222:223]
	v_mov_b32_dpp v218, v216 quad_perm:[1,0,3,2] row_mask:0xf bank_mask:0xf
	v_mov_b32_dpp v234, v232 quad_perm:[1,0,3,2] row_mask:0xf bank_mask:0xf
	v_mov_b32_dpp v219, v217 quad_perm:[1,0,3,2] row_mask:0xf bank_mask:0xf
	v_mov_b32_dpp v235, v233 quad_perm:[1,0,3,2] row_mask:0xf bank_mask:0xf
	v_perm_b32 v220, v218, v216, v201
	v_perm_b32 v236, v234, v232, v201
	v_perm_b32 v221, v219, v217, v201
	v_perm_b32 v237, v235, v233, v201
	global_store_dwordx2 v[208:209], v[220:221], off
	global_store_dwordx2 v[224:225], v[236:237], off
	v_add_u32_e32 v191, 32, v150
	v_add_u32_e32 v189, s4, v191
	s_and_b64 vcc, exec, s[8:9]
	s_mov_b64 s[38:39], -1
	s_cbranch_vccnz .LBB0_110
	v_add_u32_e32 v144, 0xffff0000, v189
	v_ashrrev_i32_e32 v144, 6, v144
	s_mov_b32 s5, 0x110000
	v_mad_i64_i32 v[144:145], s[38:39], v144, s5, 0
	s_movk_i32 s5, 0x400
	v_or3_b32 v144, v144, v188, s5
	s_mov_b64 s[38:39], 0

; template <int EPI>
; __device__ __forceinline__ void gemm_epilogue(KP P, f32x4 (&acc)[2][2][4][2], int brow, int bcol, int wr, int wc, int fr_, int fq_, const float* sRu) {
;     ...
;       for (int ai = 0; ai < 2; ++ai)
; #pragma unroll
;         for (int m = 0; m < 4; ++m) {
;           __builtin_amdgcn_sched_barrier(0);
;           unsigned lr = lrow0 + ai * 128 + m * 16;
;           int row = brow + lr;
;           size_t tb;
;           unsigned tstr;
;           if (prompt) { tb = (size_t)(row >> 12) * 1024 * 4096 + (row & 4095); tstr = 4096; }
;           else { int rs = row - MP; tb = (size_t)(rs >> 6) * 1024 * SKV + 1024 + (rs & 63); tstr = SKV; }
; #pragma unroll
;           for (int bj = 0; bj < 2; ++bj)
; #pragma unroll
;             for (int n = 0; n < 2; ++n) {
;               f32x4 v = acc[ai][bj][m][n];
;               unsigned lc = lcol0 + bj * 128 + n * 16;
;               *(f32x4*)(fdst + lr * 1024 + lc) = v;
;               unsigned c = bcol - 2048 + lc;
; #pragma unroll
;               for (int j = 0; j < 4; ++j) vt[tb + (size_t)(c + j) * tstr] = f2bf(v[j]);
;             }
;         }
.LBB0_112:
	v_lshlrev_b32_e32 v192, 10, v191
	v_mov_b32_e32 v193, v1
	v_lshl_add_u64 v[192:193], v[192:193], 2, s[34:35]
	v_lshl_add_u64 v[194:195], v[0:1], 2, v[192:193]
	v_lshl_add_u64 v[144:145], v[144:145], 1, s[36:37]
	global_store_dwordx4 v[194:195], v[110:113], off
	v_lshl_add_u64 v[194:195], v[130:131], 2, v[192:193]
	global_store_dwordx4 v[194:195], v[106:109], off
	v_lshl_add_u64 v[222:223], v[144:145], 0, v[202:203]
	v_bfe_u32 v208, v110, 16, 1
	v_bfe_u32 v224, v106, 16, 1
	v_bfe_u32 v209, v111, 16, 1
	v_bfe_u32 v225, v107, 16, 1
	v_bfe_u32 v210, v112, 16, 1
	v_bfe_u32 v226, v108, 16, 1
	v_bfe_u32 v211, v113, 16, 1
	v_bfe_u32 v227, v109, 16, 1
	v_add3_u32 v208, v110, v208, s96
	v_add3_u32 v224, v106, v224, s96
	v_add3_u32 v209, v111, v209, s96
	v_add3_u32 v225, v107, v225, s96
	v_add3_u32 v210, v112, v210, s96
	v_add3_u32 v226, v108, v226, s96
	v_add3_u32 v211, v113, v211, s96
	v_add3_u32 v227, v109, v227, s96
	v_perm_b32 v212, v209, v208, v197
	v_perm_b32 v228, v225, v224, v197
	v_perm_b32 v213, v211, v210, v197
	v_perm_b32 v229, v227, v226, v197
	v_perm_b32 v214, v213, v212, v198
	v_perm_b32 v230, v229, v228, v198
	v_mad_u64_u32 v[208:209], s[44:45], s38, v204, 0
	v_mad_u64_u32 v[224:225], s[44:45], s38, v205, 0
	s_nop 0
	v_mov_b32_dpp v215, v214 quad_perm:[2,3,0,1] row_mask:0xf bank_mask:0xf
	v_mov_b32_dpp v231, v230 quad_perm:[2,3,0,1] row_mask:0xf bank_mask:0xf
	v_perm_b32 v216, v215, v212, v199
	v_perm_b32 v232, v231, v228, v199
	v_perm_b32 v217, v215, v213, v198
	v_perm_b32 v233, v231, v229, v198
	v_lshl_add_u64 v[208:209], v[208:209], 1, v[222:223]
	v_lshl_add_u64 v[224:225], v[224:225], 1, v[222:223]
	v_mov_b32_dpp v218, v216 quad_perm:[1,0,3,2] row_mask:0xf bank_mask:0xf
	v_mov_b32_dpp v234, v232 quad_perm:[1,0,3,2] row_mask:0xf bank_mask:0xf
	v_mov_b32_dpp v219, v217 quad_perm:[1,0,3,2] row_mask:0xf bank_mask:0xf
	v_mov_b32_dpp v235, v233 quad_perm:[1,0,3,2] row_mask:0xf bank_mask:0xf
	v_perm_b32 v220, v218, v216, v201
	v_perm_b32 v236, v234, v232, v201
	v_perm_b32 v221, v219, v217, v201
	v_perm_b32 v237, v235, v233, v201
	global_store_dwordx2 v[208:209], v[220:221], off
	global_store_dwordx2 v[224:225], v[236:237], off
	v_lshl_add_u64 v[194:195], v[132:133], 2, v[192:193]
	global_store_dwordx4 v[194:195], v[46:49], off
	v_lshl_add_u64 v[192:193], v[142:143], 2, v[192:193]
	global_store_dwordx4 v[192:193], v[42:45], off
	v_add_u32_e32 v189, 48, v157
	v_and_b32_e32 v189, 63, v189
	v_bfe_u32 v208, v46, 16, 1
	v_bfe_u32 v224, v42, 16, 1
	v_bfe_u32 v209, v47, 16, 1
	v_bfe_u32 v225, v43, 16, 1
	v_bfe_u32 v210, v48, 16, 1
	v_bfe_u32 v226, v44, 16, 1
	v_bfe_u32 v211, v49, 16, 1
	v_bfe_u32 v227, v45, 16, 1
	v_add3_u32 v208, v46, v208, s96
	v_add3_u32 v224, v42, v224, s96
	v_add3_u32 v209, v47, v209, s96
	v_add3_u32 v225, v43, v225, s96
	v_add3_u32 v210, v48, v210, s96
	v_add3_u32 v226, v44, v226, s96
	v_add3_u32 v211, v49, v211, s96
	v_add3_u32 v227, v45, v227, s96
	v_perm_b32 v212, v209, v208, v197
	v_perm_b32 v228, v225, v224, v197
	v_perm_b32 v213, v211, v210, v197
	v_perm_b32 v229, v227, v226, v197
	v_perm_b32 v214, v213, v212, v198
	v_perm_b32 v230, v229, v228, v198
	v_mad_u64_u32 v[208:209], s[44:45], s38, v206, 0
	v_mad_u64_u32 v[224:225], s[44:45], s38, v207, 0
	s_nop 0
	v_mov_b32_dpp v215, v214 quad_perm:[2,3,0,1] row_mask:0xf bank_mask:0xf
	v_mov_b32_dpp v231, v230 quad_perm:[2,3,0,1] row_mask:0xf bank_mask:0xf
	v_perm_b32 v216, v215, v212, v199
	v_perm_b32 v232, v231, v228, v199
	v_perm_b32 v217, v215, v213, v198
	v_perm_b32 v233, v231, v229, v198
	v_lshl_add_u64 v[208:209], v[208:209], 1, v[222:223]
	v_lshl_add_u64 v[224:225], v[224:225], 1, v[222:223]
	v_mov_b32_dpp v218, v216 quad_perm:[1,0,3,2] row_mask:0xf bank_mask:0xf
	v_mov_b32_dpp v234, v232 quad_perm:[1,0,3,2] row_mask:0xf bank_mask:0xf
	v_mov_b32_dpp v219, v217 quad_perm:[1,0,3,2] row_mask:0xf bank_mask:0xf
	v_mov_b32_dpp v235, v233 quad_perm:[1,0,3,2] row_mask:0xf bank_mask:0xf
	v_perm_b32 v220, v218, v216, v201
	v_perm_b32 v236, v234, v232, v201
	v_perm_b32 v221, v219, v217, v201
	v_perm_b32 v237, v235, v233, v201
	global_store_dwordx2 v[208:209], v[220:221], off
	global_store_dwordx2 v[224:225], v[236:237], off
	v_add_u32_e32 v191, 48, v150
	v_add_u32_e32 v192, s4, v191
	s_and_b64 vcc, exec, s[8:9]
	s_mov_b64 s[38:39], -1
	s_cbranch_vccnz .LBB0_114
	v_add_u32_e32 v144, 0xffff0000, v192
	v_ashrrev_i32_e32 v144, 6, v144
	s_mov_b32 s5, 0x110000
	v_mad_i64_i32 v[144:145], s[38:39], v144, s5, 0
	s_movk_i32 s5, 0x400
	v_or3_b32 v144, v144, v189, s5
	s_mov_b64 s[38:39], 0

; template <int EPI>
; __device__ __forceinline__ void gemm_epilogue(KP P, f32x4 (&acc)[2][2][4][2], int brow, int bcol, int wr, int wc, int fr_, int fq_, const float* sRu) {
;     ...
;       for (int ai = 0; ai < 2; ++ai)
; #pragma unroll
;         for (int m = 0; m < 4; ++m) {
;           __builtin_amdgcn_sched_barrier(0);
;           unsigned lr = lrow0 + ai * 128 + m * 16;
;           int row = brow + lr;
;           size_t tb;
;           unsigned tstr;
;           if (prompt) { tb = (size_t)(row >> 12) * 1024 * 4096 + (row & 4095); tstr = 4096; }
;           else { int rs = row - MP; tb = (size_t)(rs >> 6) * 1024 * SKV + 1024 + (rs & 63); tstr = SKV; }
; #pragma unroll
;           for (int bj = 0; bj < 2; ++bj)
; #pragma unroll
;             for (int n = 0; n < 2; ++n) {
;               f32x4 v = acc[ai][bj][m][n];
;               unsigned lc = lcol0 + bj * 128 + n * 16;
;               *(f32x4*)(fdst + lr * 1024 + lc) = v;
;               unsigned c = bcol - 2048 + lc;
; #pragma unroll
;               for (int j = 0; j < 4; ++j) vt[tb + (size_t)(c + j) * tstr] = f2bf(v[j]);
;             }
;         }
.LBB0_116:
	v_lshlrev_b32_e32 v192, 10, v191
	v_mov_b32_e32 v193, v1
	v_lshl_add_u64 v[192:193], v[192:193], 2, s[34:35]
	v_lshl_add_u64 v[194:195], v[0:1], 2, v[192:193]
	v_lshl_add_u64 v[144:145], v[144:145], 1, s[36:37]
	global_store_dwordx4 v[194:195], v[102:105], off
	v_lshl_add_u64 v[194:195], v[130:131], 2, v[192:193]
	global_store_dwordx4 v[194:195], v[98:101], off
	v_lshl_add_u64 v[222:223], v[144:145], 0, v[202:203]
	v_bfe_u32 v208, v102, 16, 1
	v_bfe_u32 v224, v98, 16, 1
	v_bfe_u32 v209, v103, 16, 1
	v_bfe_u32 v225, v99, 16, 1
	v_bfe_u32 v210, v104, 16, 1
	v_bfe_u32 v226, v100, 16, 1
	v_bfe_u32 v211, v105, 16, 1
	v_bfe_u32 v227, v101, 16, 1
	v_add3_u32 v208, v102, v208, s96
	v_add3_u32 v224, v98, v224, s96
	v_add3_u32 v209, v103, v209, s96
	v_add3_u32 v225, v99, v225, s96
	v_add3_u32 v210, v104, v210, s96
	v_add3_u32 v226, v100, v226, s96
	v_add3_u32 v211, v105, v211, s96
	v_add3_u32 v227, v101, v227, s96
	v_perm_b32 v212, v209, v208, v197
	v_perm_b32 v228, v225, v224, v197
	v_perm_b32 v213, v211, v210, v197
	v_perm_b32 v229, v227, v226, v197
	v_perm_b32 v214, v213, v212, v198
	v_perm_b32 v230, v229, v228, v198
	v_mad_u64_u32 v[208:209], s[44:45], s38, v204, 0
	v_mad_u64_u32 v[224:225], s[44:45], s38, v205, 0
	s_nop 0
	v_mov_b32_dpp v215, v214 quad_perm:[2,3,0,1] row_mask:0xf bank_mask:0xf
	v_mov_b32_dpp v231, v230 quad_perm:[2,3,0,1] row_mask:0xf bank_mask:0xf
	v_perm_b32 v216, v215, v212, v199
	v_perm_b32 v232, v231, v228, v199
	v_perm_b32 v217, v215, v213, v198
	v_perm_b32 v233, v231, v229, v198
	v_lshl_add_u64 v[208:209], v[208:209], 1, v[222:223]
	v_lshl_add_u64 v[224:225], v[224:225], 1, v[222:223]
	v_mov_b32_dpp v218, v216 quad_perm:[1,0,3,2] row_mask:0xf bank_mask:0xf
	v_mov_b32_dpp v234, v232 quad_perm:[1,0,3,2] row_mask:0xf bank_mask:0xf
	v_mov_b32_dpp v219, v217 quad_perm:[1,0,3,2] row_mask:0xf bank_mask:0xf
	v_mov_b32_dpp v235, v233 quad_perm:[1,0,3,2] row_mask:0xf bank_mask:0xf
	v_perm_b32 v220, v218, v216, v201
	v_perm_b32 v236, v234, v232, v201
	v_perm_b32 v221, v219, v217, v201
	v_perm_b32 v237, v235, v233, v201
	global_store_dwordx2 v[208:209], v[220:221], off
	global_store_dwordx2 v[224:225], v[236:237], off
	v_lshl_add_u64 v[194:195], v[132:133], 2, v[192:193]
	global_store_dwordx4 v[194:195], v[38:41], off
	v_lshl_add_u64 v[192:193], v[142:143], 2, v[192:193]
	global_store_dwordx4 v[192:193], v[34:37], off
	v_bfe_u32 v208, v38, 16, 1
	v_bfe_u32 v224, v34, 16, 1
	v_bfe_u32 v209, v39, 16, 1
	v_bfe_u32 v225, v35, 16, 1
	v_bfe_u32 v210, v40, 16, 1
	v_bfe_u32 v226, v36, 16, 1
	v_bfe_u32 v211, v41, 16, 1
	v_bfe_u32 v227, v37, 16, 1
	v_add3_u32 v208, v38, v208, s96
	v_add3_u32 v224, v34, v224, s96
	v_add3_u32 v209, v39, v209, s96
	v_add3_u32 v225, v35, v225, s96
	v_add3_u32 v210, v40, v210, s96
	v_add3_u32 v226, v36, v226, s96
	v_add3_u32 v211, v41, v211, s96
	v_add3_u32 v227, v37, v227, s96
	v_perm_b32 v212, v209, v208, v197
	v_perm_b32 v228, v225, v224, v197
	v_perm_b32 v213, v211, v210, v197
	v_perm_b32 v229, v227, v226, v197
	v_perm_b32 v214, v213, v212, v198
	v_perm_b32 v230, v229, v228, v198
	v_mad_u64_u32 v[208:209], s[44:45], s38, v206, 0
	v_mad_u64_u32 v[224:225], s[44:45], s38, v207, 0
	s_nop 0
	v_mov_b32_dpp v215, v214 quad_perm:[2,3,0,1] row_mask:0xf bank_mask:0xf
	v_mov_b32_dpp v231, v230 quad_perm:[2,3,0,1] row_mask:0xf bank_mask:0xf
	v_perm_b32 v216, v215, v212, v199
	v_perm_b32 v232, v231, v228, v199
	v_perm_b32 v217, v215, v213, v198
	v_perm_b32 v233, v231, v229, v198
	v_lshl_add_u64 v[208:209], v[208:209], 1, v[222:223]
	v_lshl_add_u64 v[224:225], v[224:225], 1, v[222:223]
	v_mov_b32_dpp v218, v216 quad_perm:[1,0,3,2] row_mask:0xf bank_mask:0xf
	v_mov_b32_dpp v234, v232 quad_perm:[1,0,3,2] row_mask:0xf bank_mask:0xf
	v_mov_b32_dpp v219, v217 quad_perm:[1,0,3,2] row_mask:0xf bank_mask:0xf
	v_mov_b32_dpp v235, v233 quad_perm:[1,0,3,2] row_mask:0xf bank_mask:0xf
	v_perm_b32 v220, v218, v216, v201
	v_perm_b32 v236, v234, v232, v201
	v_perm_b32 v221, v219, v217, v201
	v_perm_b32 v237, v235, v233, v201
	global_store_dwordx2 v[208:209], v[220:221], off
	global_store_dwordx2 v[224:225], v[236:237], off
	v_add_u32_e32 v191, 0x80, v150
	v_add_u32_e32 v192, s4, v191
	s_and_b64 vcc, exec, s[8:9]
	s_mov_b64 s[38:39], -1
	s_cbranch_vccnz .LBB0_118
	v_add_u32_e32 v144, 0xffff0000, v192
	v_ashrrev_i32_e32 v144, 6, v144
	s_mov_b32 s5, 0x110000
	v_mad_i64_i32 v[144:145], s[38:39], v144, s5, 0
	s_movk_i32 s5, 0x400
	v_or3_b32 v144, v144, v190, s5
	s_mov_b64 s[38:39], 0

; template <int EPI>
; __device__ __forceinline__ void gemm_epilogue(KP P, f32x4 (&acc)[2][2][4][2], int brow, int bcol, int wr, int wc, int fr_, int fq_, const float* sRu) {
;     ...
;       for (int ai = 0; ai < 2; ++ai)
; #pragma unroll
;         for (int m = 0; m < 4; ++m) {
;           __builtin_amdgcn_sched_barrier(0);
;           unsigned lr = lrow0 + ai * 128 + m * 16;
;           int row = brow + lr;
;           size_t tb;
;           unsigned tstr;
;           if (prompt) { tb = (size_t)(row >> 12) * 1024 * 4096 + (row & 4095); tstr = 4096; }
;           else { int rs = row - MP; tb = (size_t)(rs >> 6) * 1024 * SKV + 1024 + (rs & 63); tstr = SKV; }
; #pragma unroll
;           for (int bj = 0; bj < 2; ++bj)
; #pragma unroll
;             for (int n = 0; n < 2; ++n) {
;               f32x4 v = acc[ai][bj][m][n];
;               unsigned lc = lcol0 + bj * 128 + n * 16;
;               *(f32x4*)(fdst + lr * 1024 + lc) = v;
;               unsigned c = bcol - 2048 + lc;
; #pragma unroll
;               for (int j = 0; j < 4; ++j) vt[tb + (size_t)(c + j) * tstr] = f2bf(v[j]);
;             }
;         }
.LBB0_120:
	v_lshlrev_b32_e32 v190, 10, v191
	v_mov_b32_e32 v191, v1
	v_lshl_add_u64 v[190:191], v[190:191], 2, s[34:35]
	v_lshl_add_u64 v[192:193], v[0:1], 2, v[190:191]
	global_store_dwordx4 v[192:193], v[94:97], off
	v_lshl_add_u64 v[144:145], v[144:145], 1, s[36:37]
	v_lshl_add_u64 v[192:193], v[130:131], 2, v[190:191]
	global_store_dwordx4 v[192:193], v[90:93], off
	v_lshl_add_u64 v[222:223], v[144:145], 0, v[202:203]
	v_bfe_u32 v208, v94, 16, 1
	v_bfe_u32 v224, v90, 16, 1
	v_bfe_u32 v209, v95, 16, 1
	v_bfe_u32 v225, v91, 16, 1
	v_bfe_u32 v210, v96, 16, 1
	v_bfe_u32 v226, v92, 16, 1
	v_bfe_u32 v211, v97, 16, 1
	v_bfe_u32 v227, v93, 16, 1
	v_add3_u32 v208, v94, v208, s96
	v_add3_u32 v224, v90, v224, s96
	v_add3_u32 v209, v95, v209, s96
	v_add3_u32 v225, v91, v225, s96
	v_add3_u32 v210, v96, v210, s96
	v_add3_u32 v226, v92, v226, s96
	v_add3_u32 v211, v97, v211, s96
	v_add3_u32 v227, v93, v227, s96
	v_perm_b32 v212, v209, v208, v197
	v_perm_b32 v228, v225, v224, v197
	v_perm_b32 v213, v211, v210, v197
	v_perm_b32 v229, v227, v226, v197
	v_perm_b32 v214, v213, v212, v198
	v_perm_b32 v230, v229, v228, v198
	v_mad_u64_u32 v[208:209], s[44:45], s38, v204, 0
	v_mad_u64_u32 v[224:225], s[44:45], s38, v205, 0
	s_nop 0
	v_mov_b32_dpp v215, v214 quad_perm:[2,3,0,1] row_mask:0xf bank_mask:0xf
	v_mov_b32_dpp v231, v230 quad_perm:[2,3,0,1] row_mask:0xf bank_mask:0xf
	v_perm_b32 v216, v215, v212, v199
	v_perm_b32 v232, v231, v228, v199
	v_perm_b32 v217, v215, v213, v198
	v_perm_b32 v233, v231, v229, v198
	v_lshl_add_u64 v[208:209], v[208:209], 1, v[222:223]
	v_lshl_add_u64 v[224:225], v[224:225], 1, v[222:223]
	v_mov_b32_dpp v218, v216 quad_perm:[1,0,3,2] row_mask:0xf bank_mask:0xf
	v_mov_b32_dpp v234, v232 quad_perm:[1,0,3,2] row_mask:0xf bank_mask:0xf
	v_mov_b32_dpp v219, v217 quad_perm:[1,0,3,2] row_mask:0xf bank_mask:0xf
	v_mov_b32_dpp v235, v233 quad_perm:[1,0,3,2] row_mask:0xf bank_mask:0xf
	v_perm_b32 v220, v218, v216, v201
	v_perm_b32 v236, v234, v232, v201
	v_perm_b32 v221, v219, v217, v201
	v_perm_b32 v237, v235, v233, v201
	global_store_dwordx2 v[208:209], v[220:221], off
	global_store_dwordx2 v[224:225], v[236:237], off
	v_lshl_add_u64 v[192:193], v[132:133], 2, v[190:191]
	global_store_dwordx4 v[192:193], v[30:33], off
	v_lshl_add_u64 v[190:191], v[142:143], 2, v[190:191]
	global_store_dwordx4 v[190:191], v[26:29], off
	v_bfe_u32 v208, v30, 16, 1
	v_bfe_u32 v224, v26, 16, 1
	v_bfe_u32 v209, v31, 16, 1
	v_bfe_u32 v225, v27, 16, 1
	v_bfe_u32 v210, v32, 16, 1
	v_bfe_u32 v226, v28, 16, 1
	v_bfe_u32 v211, v33, 16, 1
	v_bfe_u32 v227, v29, 16, 1
	v_add3_u32 v208, v30, v208, s96
	v_add3_u32 v224, v26, v224, s96
	v_add3_u32 v209, v31, v209, s96
	v_add3_u32 v225, v27, v225, s96
	v_add3_u32 v210, v32, v210, s96
	v_add3_u32 v226, v28, v226, s96
	v_add3_u32 v211, v33, v211, s96
	v_add3_u32 v227, v29, v227, s96
	v_perm_b32 v212, v209, v208, v197
	v_perm_b32 v228, v225, v224, v197
	v_perm_b32 v213, v211, v210, v197
	v_perm_b32 v229, v227, v226, v197
	v_perm_b32 v214, v213, v212, v198
	v_perm_b32 v230, v229, v228, v198
	v_mad_u64_u32 v[208:209], s[44:45], s38, v206, 0
	v_mad_u64_u32 v[224:225], s[44:45], s38, v207, 0
	s_nop 0
	v_mov_b32_dpp v215, v214 quad_perm:[2,3,0,1] row_mask:0xf bank_mask:0xf
	v_mov_b32_dpp v231, v230 quad_perm:[2,3,0,1] row_mask:0xf bank_mask:0xf
	v_perm_b32 v216, v215, v212, v199
	v_perm_b32 v232, v231, v228, v199
	v_perm_b32 v217, v215, v213, v198
	v_perm_b32 v233, v231, v229, v198
	v_lshl_add_u64 v[208:209], v[208:209], 1, v[222:223]
	v_lshl_add_u64 v[224:225], v[224:225], 1, v[222:223]
	v_mov_b32_dpp v218, v216 quad_perm:[1,0,3,2] row_mask:0xf bank_mask:0xf
	v_mov_b32_dpp v234, v232 quad_perm:[1,0,3,2] row_mask:0xf bank_mask:0xf
	v_mov_b32_dpp v219, v217 quad_perm:[1,0,3,2] row_mask:0xf bank_mask:0xf
	v_mov_b32_dpp v235, v233 quad_perm:[1,0,3,2] row_mask:0xf bank_mask:0xf
	v_perm_b32 v220, v218, v216, v201
	v_perm_b32 v236, v234, v232, v201
	v_perm_b32 v221, v219, v217, v201
	v_perm_b32 v237, v235, v233, v201
	global_store_dwordx2 v[208:209], v[220:221], off
	global_store_dwordx2 v[224:225], v[236:237], off
	v_add_u32_e32 v190, 0x90, v150
	v_add_u32_e32 v191, s4, v190
	s_and_b64 vcc, exec, s[8:9]
	s_mov_b64 s[38:39], -1
	s_cbranch_vccnz .LBB0_122
	v_add_u32_e32 v144, 0xffff0000, v191
	v_ashrrev_i32_e32 v144, 6, v144
	s_mov_b32 s5, 0x110000
	v_mad_i64_i32 v[144:145], s[38:39], v144, s5, 0
	s_movk_i32 s5, 0x400
	v_or3_b32 v144, v144, v187, s5
	s_mov_b64 s[38:39], 0

; template <int EPI>
; __device__ __forceinline__ void gemm_epilogue(KP P, f32x4 (&acc)[2][2][4][2], int brow, int bcol, int wr, int wc, int fr_, int fq_, const float* sRu) {
;     ...
;       for (int ai = 0; ai < 2; ++ai)
; #pragma unroll
;         for (int m = 0; m < 4; ++m) {
;           __builtin_amdgcn_sched_barrier(0);
;           unsigned lr = lrow0 + ai * 128 + m * 16;
;           int row = brow + lr;
;           size_t tb;
;           unsigned tstr;
;           if (prompt) { tb = (size_t)(row >> 12) * 1024 * 4096 + (row & 4095); tstr = 4096; }
;           else { int rs = row - MP; tb = (size_t)(rs >> 6) * 1024 * SKV + 1024 + (rs & 63); tstr = SKV; }
; #pragma unroll
;           for (int bj = 0; bj < 2; ++bj)
; #pragma unroll
;             for (int n = 0; n < 2; ++n) {
;               f32x4 v = acc[ai][bj][m][n];
;               unsigned lc = lcol0 + bj * 128 + n * 16;
;               *(f32x4*)(fdst + lr * 1024 + lc) = v;
;               unsigned c = bcol - 2048 + lc;
; #pragma unroll
;               for (int j = 0; j < 4; ++j) vt[tb + (size_t)(c + j) * tstr] = f2bf(v[j]);
;             }
;         }
.LBB0_124:
	v_lshlrev_b32_e32 v190, 10, v190
	v_mov_b32_e32 v191, v1
	v_lshl_add_u64 v[190:191], v[190:191], 2, s[34:35]
	v_lshl_add_u64 v[192:193], v[0:1], 2, v[190:191]
	v_lshl_add_u64 v[144:145], v[144:145], 1, s[36:37]
	global_store_dwordx4 v[192:193], v[86:89], off
	v_lshl_add_u64 v[192:193], v[130:131], 2, v[190:191]
	global_store_dwordx4 v[192:193], v[82:85], off
	v_lshl_add_u64 v[222:223], v[144:145], 0, v[202:203]
	v_bfe_u32 v208, v86, 16, 1
	v_bfe_u32 v224, v82, 16, 1
	v_bfe_u32 v209, v87, 16, 1
	v_bfe_u32 v225, v83, 16, 1
	v_bfe_u32 v210, v88, 16, 1
	v_bfe_u32 v226, v84, 16, 1
	v_bfe_u32 v211, v89, 16, 1
	v_bfe_u32 v227, v85, 16, 1
	v_add3_u32 v208, v86, v208, s96
	v_add3_u32 v224, v82, v224, s96
	v_add3_u32 v209, v87, v209, s96
	v_add3_u32 v225, v83, v225, s96
	v_add3_u32 v210, v88, v210, s96
	v_add3_u32 v226, v84, v226, s96
	v_add3_u32 v211, v89, v211, s96
	v_add3_u32 v227, v85, v227, s96
	v_perm_b32 v212, v209, v208, v197
	v_perm_b32 v228, v225, v224, v197
	v_perm_b32 v213, v211, v210, v197
	v_perm_b32 v229, v227, v226, v197
	v_perm_b32 v214, v213, v212, v198
	v_perm_b32 v230, v229, v228, v198
	v_mad_u64_u32 v[208:209], s[44:45], s38, v204, 0
	v_mad_u64_u32 v[224:225], s[44:45], s38, v205, 0
	s_nop 0
	v_mov_b32_dpp v215, v214 quad_perm:[2,3,0,1] row_mask:0xf bank_mask:0xf
	v_mov_b32_dpp v231, v230 quad_perm:[2,3,0,1] row_mask:0xf bank_mask:0xf
	v_perm_b32 v216, v215, v212, v199
	v_perm_b32 v232, v231, v228, v199
	v_perm_b32 v217, v215, v213, v198
	v_perm_b32 v233, v231, v229, v198
	v_lshl_add_u64 v[208:209], v[208:209], 1, v[222:223]
	v_lshl_add_u64 v[224:225], v[224:225], 1, v[222:223]
	v_mov_b32_dpp v218, v216 quad_perm:[1,0,3,2] row_mask:0xf bank_mask:0xf
	v_mov_b32_dpp v234, v232 quad_perm:[1,0,3,2] row_mask:0xf bank_mask:0xf
	v_mov_b32_dpp v219, v217 quad_perm:[1,0,3,2] row_mask:0xf bank_mask:0xf
	v_mov_b32_dpp v235, v233 quad_perm:[1,0,3,2] row_mask:0xf bank_mask:0xf
	v_perm_b32 v220, v218, v216, v201
	v_perm_b32 v236, v234, v232, v201
	v_perm_b32 v221, v219, v217, v201
	v_perm_b32 v237, v235, v233, v201
	global_store_dwordx2 v[208:209], v[220:221], off
	global_store_dwordx2 v[224:225], v[236:237], off
	v_lshl_add_u64 v[192:193], v[132:133], 2, v[190:191]
	global_store_dwordx4 v[192:193], v[22:25], off
	v_lshl_add_u64 v[190:191], v[142:143], 2, v[190:191]
	global_store_dwordx4 v[190:191], v[18:21], off
	v_bfe_u32 v208, v22, 16, 1
	v_bfe_u32 v224, v18, 16, 1
	v_bfe_u32 v209, v23, 16, 1
	v_bfe_u32 v225, v19, 16, 1
	v_bfe_u32 v210, v24, 16, 1
	v_bfe_u32 v226, v20, 16, 1
	v_bfe_u32 v211, v25, 16, 1
	v_bfe_u32 v227, v21, 16, 1
	v_add3_u32 v208, v22, v208, s96
	v_add3_u32 v224, v18, v224, s96
	v_add3_u32 v209, v23, v209, s96
	v_add3_u32 v225, v19, v225, s96
	v_add3_u32 v210, v24, v210, s96
	v_add3_u32 v226, v20, v226, s96
	v_add3_u32 v211, v25, v211, s96
	v_add3_u32 v227, v21, v227, s96
	v_perm_b32 v212, v209, v208, v197
	v_perm_b32 v228, v225, v224, v197
	v_perm_b32 v213, v211, v210, v197
	v_perm_b32 v229, v227, v226, v197
	v_perm_b32 v214, v213, v212, v198
	v_perm_b32 v230, v229, v228, v198
	v_mad_u64_u32 v[208:209], s[44:45], s38, v206, 0
	v_mad_u64_u32 v[224:225], s[44:45], s38, v207, 0
	s_nop 0
	v_mov_b32_dpp v215, v214 quad_perm:[2,3,0,1] row_mask:0xf bank_mask:0xf
	v_mov_b32_dpp v231, v230 quad_perm:[2,3,0,1] row_mask:0xf bank_mask:0xf
	v_perm_b32 v216, v215, v212, v199
	v_perm_b32 v232, v231, v228, v199
	v_perm_b32 v217, v215, v213, v198
	v_perm_b32 v233, v231, v229, v198
	v_lshl_add_u64 v[208:209], v[208:209], 1, v[222:223]
	v_lshl_add_u64 v[224:225], v[224:225], 1, v[222:223]
	v_mov_b32_dpp v218, v216 quad_perm:[1,0,3,2] row_mask:0xf bank_mask:0xf
	v_mov_b32_dpp v234, v232 quad_perm:[1,0,3,2] row_mask:0xf bank_mask:0xf
	v_mov_b32_dpp v219, v217 quad_perm:[1,0,3,2] row_mask:0xf bank_mask:0xf
	v_mov_b32_dpp v235, v233 quad_perm:[1,0,3,2] row_mask:0xf bank_mask:0xf
	v_perm_b32 v220, v218, v216, v201
	v_perm_b32 v236, v234, v232, v201
	v_perm_b32 v221, v219, v217, v201
	v_perm_b32 v237, v235, v233, v201
	global_store_dwordx2 v[208:209], v[220:221], off
	global_store_dwordx2 v[224:225], v[236:237], off
	v_add_u32_e32 v187, 0xa0, v150
	v_add_u32_e32 v190, s4, v187
	s_and_b64 vcc, exec, s[8:9]
	s_mov_b64 s[38:39], -1
	s_cbranch_vccnz .LBB0_126
	v_add_u32_e32 v144, 0xffff0000, v190
	v_ashrrev_i32_e32 v144, 6, v144
	s_mov_b32 s5, 0x110000
	v_mad_i64_i32 v[144:145], s[38:39], v144, s5, 0
	s_movk_i32 s5, 0x400
	v_or3_b32 v144, v144, v188, s5
	s_mov_b64 s[38:39], 0

; template <int EPI>
; __device__ __forceinline__ void gemm_epilogue(KP P, f32x4 (&acc)[2][2][4][2], int brow, int bcol, int wr, int wc, int fr_, int fq_, const float* sRu) {
;     ...
;       for (int ai = 0; ai < 2; ++ai)
; #pragma unroll
;         for (int m = 0; m < 4; ++m) {
;           __builtin_amdgcn_sched_barrier(0);
;           unsigned lr = lrow0 + ai * 128 + m * 16;
;           int row = brow + lr;
;           size_t tb;
;           unsigned tstr;
;           if (prompt) { tb = (size_t)(row >> 12) * 1024 * 4096 + (row & 4095); tstr = 4096; }
;           else { int rs = row - MP; tb = (size_t)(rs >> 6) * 1024 * SKV + 1024 + (rs & 63); tstr = SKV; }
; #pragma unroll
;           for (int bj = 0; bj < 2; ++bj)
; #pragma unroll
;             for (int n = 0; n < 2; ++n) {
;               f32x4 v = acc[ai][bj][m][n];
;               unsigned lc = lcol0 + bj * 128 + n * 16;
;               *(f32x4*)(fdst + lr * 1024 + lc) = v;
;               unsigned c = bcol - 2048 + lc;
; #pragma unroll
;               for (int j = 0; j < 4; ++j) vt[tb + (size_t)(c + j) * tstr] = f2bf(v[j]);
;             }
;         }
.LBB0_128:
	v_lshlrev_b32_e32 v190, 10, v187
	v_mov_b32_e32 v191, v1
	v_lshl_add_u64 v[190:191], v[190:191], 2, s[34:35]
	v_lshl_add_u64 v[192:193], v[0:1], 2, v[190:191]
	v_lshl_add_u64 v[144:145], v[144:145], 1, s[36:37]
	global_store_dwordx4 v[192:193], v[78:81], off
	v_lshl_add_u64 v[192:193], v[130:131], 2, v[190:191]
	global_store_dwordx4 v[192:193], v[74:77], off
	v_lshl_add_u64 v[222:223], v[144:145], 0, v[202:203]
	v_bfe_u32 v208, v78, 16, 1
	v_bfe_u32 v224, v74, 16, 1
	v_bfe_u32 v209, v79, 16, 1
	v_bfe_u32 v225, v75, 16, 1
	v_bfe_u32 v210, v80, 16, 1
	v_bfe_u32 v226, v76, 16, 1
	v_bfe_u32 v211, v81, 16, 1
	v_bfe_u32 v227, v77, 16, 1
	v_add3_u32 v208, v78, v208, s96
	v_add3_u32 v224, v74, v224, s96
	v_add3_u32 v209, v79, v209, s96
	v_add3_u32 v225, v75, v225, s96
	v_add3_u32 v210, v80, v210, s96
	v_add3_u32 v226, v76, v226, s96
	v_add3_u32 v211, v81, v211, s96
	v_add3_u32 v227, v77, v227, s96
	v_perm_b32 v212, v209, v208, v197
	v_perm_b32 v228, v225, v224, v197
	v_perm_b32 v213, v211, v210, v197
	v_perm_b32 v229, v227, v226, v197
	v_perm_b32 v214, v213, v212, v198
	v_perm_b32 v230, v229, v228, v198
	v_mad_u64_u32 v[208:209], s[44:45], s38, v204, 0
	v_mad_u64_u32 v[224:225], s[44:45], s38, v205, 0
	s_nop 0
	v_mov_b32_dpp v215, v214 quad_perm:[2,3,0,1] row_mask:0xf bank_mask:0xf
	v_mov_b32_dpp v231, v230 quad_perm:[2,3,0,1] row_mask:0xf bank_mask:0xf
	v_perm_b32 v216, v215, v212, v199
	v_perm_b32 v232, v231, v228, v199
	v_perm_b32 v217, v215, v213, v198
	v_perm_b32 v233, v231, v229, v198
	v_lshl_add_u64 v[208:209], v[208:209], 1, v[222:223]
	v_lshl_add_u64 v[224:225], v[224:225], 1, v[222:223]
	v_mov_b32_dpp v218, v216 quad_perm:[1,0,3,2] row_mask:0xf bank_mask:0xf
	v_mov_b32_dpp v234, v232 quad_perm:[1,0,3,2] row_mask:0xf bank_mask:0xf
	v_mov_b32_dpp v219, v217 quad_perm:[1,0,3,2] row_mask:0xf bank_mask:0xf
	v_mov_b32_dpp v235, v233 quad_perm:[1,0,3,2] row_mask:0xf bank_mask:0xf
	v_perm_b32 v220, v218, v216, v201
	v_perm_b32 v236, v234, v232, v201
	v_perm_b32 v221, v219, v217, v201
	v_perm_b32 v237, v235, v233, v201
	global_store_dwordx2 v[208:209], v[220:221], off
	global_store_dwordx2 v[224:225], v[236:237], off
	v_lshl_add_u64 v[192:193], v[132:133], 2, v[190:191]
	global_store_dwordx4 v[192:193], v[14:17], off
	v_lshl_add_u64 v[190:191], v[142:143], 2, v[190:191]
	global_store_dwordx4 v[190:191], v[10:13], off
	v_bfe_u32 v208, v14, 16, 1
	v_bfe_u32 v224, v10, 16, 1
	v_bfe_u32 v209, v15, 16, 1
	v_bfe_u32 v225, v11, 16, 1
	v_bfe_u32 v210, v16, 16, 1
	v_bfe_u32 v226, v12, 16, 1
	v_bfe_u32 v211, v17, 16, 1
	v_bfe_u32 v227, v13, 16, 1
	v_add3_u32 v208, v14, v208, s96
	v_add3_u32 v224, v10, v224, s96
	v_add3_u32 v209, v15, v209, s96
	v_add3_u32 v225, v11, v225, s96
	v_add3_u32 v210, v16, v210, s96
	v_add3_u32 v226, v12, v226, s96
	v_add3_u32 v211, v17, v211, s96
	v_add3_u32 v227, v13, v227, s96
	v_perm_b32 v212, v209, v208, v197
	v_perm_b32 v228, v225, v224, v197
	v_perm_b32 v213, v211, v210, v197
	v_perm_b32 v229, v227, v226, v197
	v_perm_b32 v214, v213, v212, v198
	v_perm_b32 v230, v229, v228, v198
	v_mad_u64_u32 v[208:209], s[44:45], s38, v206, 0
	v_mad_u64_u32 v[224:225], s[44:45], s38, v207, 0
	s_nop 0
	v_mov_b32_dpp v215, v214 quad_perm:[2,3,0,1] row_mask:0xf bank_mask:0xf
	v_mov_b32_dpp v231, v230 quad_perm:[2,3,0,1] row_mask:0xf bank_mask:0xf
	v_perm_b32 v216, v215, v212, v199
	v_perm_b32 v232, v231, v228, v199
	v_perm_b32 v217, v215, v213, v198
	v_perm_b32 v233, v231, v229, v198
	v_lshl_add_u64 v[208:209], v[208:209], 1, v[222:223]
	v_lshl_add_u64 v[224:225], v[224:225], 1, v[222:223]
	v_mov_b32_dpp v218, v216 quad_perm:[1,0,3,2] row_mask:0xf bank_mask:0xf
	v_mov_b32_dpp v234, v232 quad_perm:[1,0,3,2] row_mask:0xf bank_mask:0xf
	v_mov_b32_dpp v219, v217 quad_perm:[1,0,3,2] row_mask:0xf bank_mask:0xf
	v_mov_b32_dpp v235, v233 quad_perm:[1,0,3,2] row_mask:0xf bank_mask:0xf
	v_perm_b32 v220, v218, v216, v201
	v_perm_b32 v236, v234, v232, v201
	v_perm_b32 v221, v219, v217, v201
	v_perm_b32 v237, v235, v233, v201
	global_store_dwordx2 v[208:209], v[220:221], off
	global_store_dwordx2 v[224:225], v[236:237], off
	v_add_u32_e32 v150, 0xb0, v150
	v_add_u32_e32 v187, s4, v150
	s_and_b64 vcc, exec, s[8:9]
	s_mov_b64 s[8:9], -1
	s_cbranch_vccnz .LBB0_130
	v_add_u32_e32 v144, 0xffff0000, v187
	v_ashrrev_i32_e32 v144, 6, v144
	s_mov_b32 s5, 0x110000
	v_mad_i64_i32 v[144:145], s[8:9], v144, s5, 0
	s_movk_i32 s5, 0x400
	v_or3_b32 v144, v144, v189, s5
	s_mov_b64 s[8:9], 0

; template <int EPI>
; __device__ __forceinline__ void gemm_epilogue(KP P, f32x4 (&acc)[2][2][4][2], int brow, int bcol, int wr, int wc, int fr_, int fq_, const float* sRu) {
;     ...
;       for (int ai = 0; ai < 2; ++ai)
; #pragma unroll
;         for (int m = 0; m < 4; ++m) {
;           __builtin_amdgcn_sched_barrier(0);
;           unsigned lr = lrow0 + ai * 128 + m * 16;
;           int row = brow + lr;
;           size_t tb;
;           unsigned tstr;
;           if (prompt) { tb = (size_t)(row >> 12) * 1024 * 4096 + (row & 4095); tstr = 4096; }
;           else { int rs = row - MP; tb = (size_t)(rs >> 6) * 1024 * SKV + 1024 + (rs & 63); tstr = SKV; }
; #pragma unroll
;           for (int bj = 0; bj < 2; ++bj)
; #pragma unroll
;             for (int n = 0; n < 2; ++n) {
;               f32x4 v = acc[ai][bj][m][n];
;               unsigned lc = lcol0 + bj * 128 + n * 16;
;               *(f32x4*)(fdst + lr * 1024 + lc) = v;
;               unsigned c = bcol - 2048 + lc;
; #pragma unroll
;               for (int j = 0; j < 4; ++j) vt[tb + (size_t)(c + j) * tstr] = f2bf(v[j]);
;             }
;         }
.LBB0_132:
	v_lshlrev_b32_e32 v188, 10, v150
	v_mov_b32_e32 v189, v1
	v_lshl_add_u64 v[188:189], v[188:189], 2, s[34:35]
	v_lshl_add_u64 v[144:145], v[144:145], 1, s[36:37]
	v_lshl_add_u64 v[190:191], v[0:1], 2, v[188:189]
	global_store_dwordx4 v[190:191], v[70:73], off
	v_lshl_add_u64 v[130:131], v[130:131], 2, v[188:189]
	global_store_dwordx4 v[130:131], v[66:69], off
	v_lshl_add_u64 v[222:223], v[144:145], 0, v[202:203]
	v_bfe_u32 v208, v70, 16, 1
	v_bfe_u32 v224, v66, 16, 1
	v_bfe_u32 v209, v71, 16, 1
	v_bfe_u32 v225, v67, 16, 1
	v_bfe_u32 v210, v72, 16, 1
	v_bfe_u32 v226, v68, 16, 1
	v_bfe_u32 v211, v73, 16, 1
	v_bfe_u32 v227, v69, 16, 1
	v_add3_u32 v208, v70, v208, s96
	v_add3_u32 v224, v66, v224, s96
	v_add3_u32 v209, v71, v209, s96
	v_add3_u32 v225, v67, v225, s96
	v_add3_u32 v210, v72, v210, s96
	v_add3_u32 v226, v68, v226, s96
	v_add3_u32 v211, v73, v211, s96
	v_add3_u32 v227, v69, v227, s96
	v_perm_b32 v212, v209, v208, v197
	v_perm_b32 v228, v225, v224, v197
	v_perm_b32 v213, v211, v210, v197
	v_perm_b32 v229, v227, v226, v197
	v_perm_b32 v214, v213, v212, v198
	v_perm_b32 v230, v229, v228, v198
	v_mad_u64_u32 v[208:209], s[34:35], s8, v204, 0
	v_mad_u64_u32 v[224:225], s[34:35], s8, v205, 0
	s_nop 0
	v_mov_b32_dpp v215, v214 quad_perm:[2,3,0,1] row_mask:0xf bank_mask:0xf
	v_mov_b32_dpp v231, v230 quad_perm:[2,3,0,1] row_mask:0xf bank_mask:0xf
	v_perm_b32 v216, v215, v212, v199
	v_perm_b32 v232, v231, v228, v199
	v_perm_b32 v217, v215, v213, v198
	v_perm_b32 v233, v231, v229, v198
	v_lshl_add_u64 v[208:209], v[208:209], 1, v[222:223]
	v_lshl_add_u64 v[224:225], v[224:225], 1, v[222:223]
	v_mov_b32_dpp v218, v216 quad_perm:[1,0,3,2] row_mask:0xf bank_mask:0xf
	v_mov_b32_dpp v234, v232 quad_perm:[1,0,3,2] row_mask:0xf bank_mask:0xf
	v_mov_b32_dpp v219, v217 quad_perm:[1,0,3,2] row_mask:0xf bank_mask:0xf
	v_mov_b32_dpp v235, v233 quad_perm:[1,0,3,2] row_mask:0xf bank_mask:0xf
	v_perm_b32 v220, v218, v216, v201
	v_perm_b32 v236, v234, v232, v201
	v_perm_b32 v221, v219, v217, v201
	v_perm_b32 v237, v235, v233, v201
	global_store_dwordx2 v[208:209], v[220:221], off
	global_store_dwordx2 v[224:225], v[236:237], off
	v_lshl_add_u64 v[130:131], v[132:133], 2, v[188:189]
	global_store_dwordx4 v[130:131], v[6:9], off
	v_lshl_add_u64 v[130:131], v[142:143], 2, v[188:189]
	global_store_dwordx4 v[130:131], v[2:5], off
	v_bfe_u32 v208, v6, 16, 1
	v_bfe_u32 v224, v2, 16, 1
	v_bfe_u32 v209, v7, 16, 1
	v_bfe_u32 v225, v3, 16, 1
	v_bfe_u32 v210, v8, 16, 1
	v_bfe_u32 v226, v4, 16, 1
	v_bfe_u32 v211, v9, 16, 1
	v_bfe_u32 v227, v5, 16, 1
	v_add3_u32 v208, v6, v208, s96
	v_add3_u32 v224, v2, v224, s96
	v_add3_u32 v209, v7, v209, s96
	v_add3_u32 v225, v3, v225, s96
	v_add3_u32 v210, v8, v210, s96
	v_add3_u32 v226, v4, v226, s96
	v_add3_u32 v211, v9, v211, s96
	v_add3_u32 v227, v5, v227, s96
	v_perm_b32 v212, v209, v208, v197
	v_perm_b32 v228, v225, v224, v197
	v_perm_b32 v213, v211, v210, v197
	v_perm_b32 v229, v227, v226, v197
	v_perm_b32 v214, v213, v212, v198
	v_perm_b32 v230, v229, v228, v198
	v_mad_u64_u32 v[208:209], s[34:35], s8, v206, 0
	v_mad_u64_u32 v[224:225], s[34:35], s8, v207, 0
	s_nop 0
	v_mov_b32_dpp v215, v214 quad_perm:[2,3,0,1] row_mask:0xf bank_mask:0xf
	v_mov_b32_dpp v231, v230 quad_perm:[2,3,0,1] row_mask:0xf bank_mask:0xf
	v_perm_b32 v216, v215, v212, v199
	v_perm_b32 v232, v231, v228, v199
	v_perm_b32 v217, v215, v213, v198
	v_perm_b32 v233, v231, v229, v198
	v_lshl_add_u64 v[208:209], v[208:209], 1, v[222:223]
	v_lshl_add_u64 v[224:225], v[224:225], 1, v[222:223]
	v_mov_b32_dpp v218, v216 quad_perm:[1,0,3,2] row_mask:0xf bank_mask:0xf
	v_mov_b32_dpp v234, v232 quad_perm:[1,0,3,2] row_mask:0xf bank_mask:0xf
	v_mov_b32_dpp v219, v217 quad_perm:[1,0,3,2] row_mask:0xf bank_mask:0xf
	v_mov_b32_dpp v235, v233 quad_perm:[1,0,3,2] row_mask:0xf bank_mask:0xf
	v_perm_b32 v220, v218, v216, v201
	v_perm_b32 v236, v234, v232, v201
	v_perm_b32 v221, v219, v217, v201
	v_perm_b32 v237, v235, v233, v201
	global_store_dwordx2 v[208:209], v[220:221], off
	global_store_dwordx2 v[224:225], v[236:237], off
	s_mov_b64 s[8:9], 0

; __device__ __forceinline__ void phase_ssd(KP P, char* smem, const int wv) {
;     ...
;       {
;         const float dec = __expf(a63);
; #pragma unroll
;         for (int nt = 0; nt < 8; ++nt) hacc[nt] *= dec;
; #pragma unroll
;         for (int ks = 0; ks < 2; ++ks) {
;           const int j0 = ks * 32 + fqc * 8;
;           bf16x8 xr = lds_b128(xrow + j0);
;           f32x4 w0 = *(const f32x4*)(myW + j0), w1 = *(const f32x4*)(myW + j0 + 4);
;           u32x4 xu = __builtin_bit_cast(u32x4, xr);
;           u32x4 pk;
;           pk[0] = cvt_pk_bf16(__uint_as_float(xu[0] << 16) * w0[0], __uint_as_float(xu[0] & 0xffff0000u) * w0[1]);
;           pk[1] = cvt_pk_bf16(__uint_as_float(xu[1] << 16) * w0[2], __uint_as_float(xu[1] & 0xffff0000u) * w0[3]);
;           pk[2] = cvt_pk_bf16(__uint_as_float(xu[2] << 16) * w1[0], __uint_as_float(xu[2] & 0xffff0000u) * w1[1]);
;           pk[3] = cvt_pk_bf16(__uint_as_float(xu[3] << 16) * w1[2], __uint_as_float(xu[3] & 0xffff0000u) * w1[3]);
;           bf16x8 af = __builtin_bit_cast(bf16x8, pk);
; #pragma unroll
;           for (int nt = 0; nt < 8; ++nt) {
;             bf16x8 b = lds_b128(sBT + (nt * 16 + frc) * S_LDT + j0);
;             hacc[nt] = mfma16(af, b, hacc[nt]);
;           }
;         }
.LBB0_441:
	v_mul_f32_e32 v80, s49, v175
	v_exp_f32_e32 v80, v80
	v_lshlrev_b32_e32 v95, 1, v94
	v_lshl_add_u32 v94, v94, 2, s70
	v_add3_u32 v95, s64, v95, v97
	v_pk_mul_f32 v[30:31], v[30:31], v[80:81] op_sel_hi:[1,0]
	v_pk_mul_f32 v[28:29], v[28:29], v[80:81] op_sel_hi:[1,0]
	v_pk_mul_f32 v[34:35], v[34:35], v[80:81] op_sel_hi:[1,0]
	v_pk_mul_f32 v[32:33], v[32:33], v[80:81] op_sel_hi:[1,0]
	v_pk_mul_f32 v[22:23], v[22:23], v[80:81] op_sel_hi:[1,0]
	v_pk_mul_f32 v[20:21], v[20:21], v[80:81] op_sel_hi:[1,0]
	v_pk_mul_f32 v[26:27], v[26:27], v[80:81] op_sel_hi:[1,0]
	v_pk_mul_f32 v[24:25], v[24:25], v[80:81] op_sel_hi:[1,0]
	v_pk_mul_f32 v[14:15], v[14:15], v[80:81] op_sel_hi:[1,0]
	v_pk_mul_f32 v[12:13], v[12:13], v[80:81] op_sel_hi:[1,0]
	v_pk_mul_f32 v[18:19], v[18:19], v[80:81] op_sel_hi:[1,0]
	v_pk_mul_f32 v[16:17], v[16:17], v[80:81] op_sel_hi:[1,0]
	v_pk_mul_f32 v[6:7], v[6:7], v[80:81] op_sel_hi:[1,0]
	v_pk_mul_f32 v[4:5], v[4:5], v[80:81] op_sel_hi:[1,0]
	v_pk_mul_f32 v[10:11], v[10:11], v[80:81] op_sel_hi:[1,0]
	v_pk_mul_f32 v[8:9], v[8:9], v[80:81] op_sel_hi:[1,0]
	ds_read_b128 v[84:87], v94
	ds_read_b128 v[88:91], v94 offset:16
	ds_read_b128 v[104:107], v94 offset:128
	ds_read_b128 v[108:111], v94 offset:144
	ds_read_b128 v[156:159], v95 offset:34816
	ds_read_b128 v[160:163], v95 offset:37120
	ds_read_b128 v[208:211], v95 offset:39424
	ds_read_b128 v[212:215], v95 offset:41728
	ds_read_b128 v[216:219], v95 offset:44032
	ds_read_b128 v[220:223], v95 offset:46336
	ds_read_b128 v[224:227], v95 offset:48640
	ds_read_b128 v[236:239], v95 offset:50944
	s_waitcnt lgkmcnt(8)
	v_lshlrev_b32_e32 v96, 16, v228
	v_and_b32_e32 v97, 0xffff0000, v228
	v_mul_f32_e32 v96, v84, v96
	v_mul_f32_e32 v97, v85, v97
	v_cvt_pk_bf16_f32 v80, v96, v97
	v_lshlrev_b32_e32 v96, 16, v229
	v_and_b32_e32 v97, 0xffff0000, v229
	v_mul_f32_e32 v96, v86, v96
	v_mul_f32_e32 v97, v87, v97
	v_cvt_pk_bf16_f32 v81, v96, v97
	v_lshlrev_b32_e32 v96, 16, v230
	v_and_b32_e32 v97, 0xffff0000, v230
	v_mul_f32_e32 v96, v88, v96
	v_mul_f32_e32 v97, v89, v97
	v_cvt_pk_bf16_f32 v82, v96, v97
	v_lshlrev_b32_e32 v96, 16, v231
	v_and_b32_e32 v97, 0xffff0000, v231
	v_mul_f32_e32 v96, v90, v96
	v_mul_f32_e32 v97, v91, v97
	v_cvt_pk_bf16_f32 v83, v96, v97
	v_lshlrev_b32_e32 v96, 16, v232
	v_and_b32_e32 v97, 0xffff0000, v232
	v_mul_f32_e32 v96, v104, v96
	v_mul_f32_e32 v97, v105, v97
	v_cvt_pk_bf16_f32 v100, v96, v97
	v_lshlrev_b32_e32 v96, 16, v233
	v_and_b32_e32 v97, 0xffff0000, v233
	v_mul_f32_e32 v96, v106, v96
	v_mul_f32_e32 v97, v107, v97
	v_cvt_pk_bf16_f32 v101, v96, v97
	v_lshlrev_b32_e32 v96, 16, v234
	v_and_b32_e32 v97, 0xffff0000, v234
	v_mul_f32_e32 v96, v108, v96
	v_mul_f32_e32 v97, v109, v97
	v_cvt_pk_bf16_f32 v102, v96, v97
	v_lshlrev_b32_e32 v96, 16, v235
	v_and_b32_e32 v97, 0xffff0000, v235
	v_mul_f32_e32 v96, v110, v96
	v_mul_f32_e32 v97, v111, v97
	v_cvt_pk_bf16_f32 v103, v96, v97
	s_waitcnt lgkmcnt(7)
	v_mfma_f32_16x16x32_bf16 v[28:31], v[80:83], v[156:159], v[28:31]
	ds_read_b128 v[156:159], v95 offset:34880
	s_waitcnt lgkmcnt(7)
	v_mfma_f32_16x16x32_bf16 v[32:35], v[80:83], v[160:163], v[32:35]
	ds_read_b128 v[160:163], v95 offset:37184
	s_waitcnt lgkmcnt(7)
	v_mfma_f32_16x16x32_bf16 v[20:23], v[80:83], v[208:211], v[20:23]
	ds_read_b128 v[208:211], v95 offset:39488
	s_waitcnt lgkmcnt(7)
	v_mfma_f32_16x16x32_bf16 v[24:27], v[80:83], v[212:215], v[24:27]
	ds_read_b128 v[212:215], v95 offset:41792
	s_waitcnt lgkmcnt(7)
	v_mfma_f32_16x16x32_bf16 v[12:15], v[80:83], v[216:219], v[12:15]
	ds_read_b128 v[216:219], v95 offset:44096
	s_waitcnt lgkmcnt(7)
	v_mfma_f32_16x16x32_bf16 v[16:19], v[80:83], v[220:223], v[16:19]
	ds_read_b128 v[220:223], v95 offset:46400
	s_waitcnt lgkmcnt(7)
	v_mfma_f32_16x16x32_bf16 v[4:7], v[80:83], v[224:227], v[4:7]
	ds_read_b128 v[224:227], v95 offset:48704
	s_waitcnt lgkmcnt(7)
	v_mfma_f32_16x16x32_bf16 v[8:11], v[80:83], v[236:239], v[8:11]
	ds_read_b128 v[236:239], v95 offset:51008
	s_waitcnt lgkmcnt(7)
	v_mfma_f32_16x16x32_bf16 v[28:31], v[100:103], v[156:159], v[28:31]
	s_waitcnt lgkmcnt(6)
	v_mfma_f32_16x16x32_bf16 v[32:35], v[100:103], v[160:163], v[32:35]
	s_waitcnt lgkmcnt(5)
	v_mfma_f32_16x16x32_bf16 v[20:23], v[100:103], v[208:211], v[20:23]
	s_waitcnt lgkmcnt(4)
	v_mfma_f32_16x16x32_bf16 v[24:27], v[100:103], v[212:215], v[24:27]
	s_waitcnt lgkmcnt(3)
; __device__ __forceinline__ void phase_ssd(KP P, char* smem, const int wv) {
;     ...
; #pragma unroll
;           for (int nt = 0; nt < 8; ++nt) {
;             bf16x8 b = lds_b128(sBT + (nt * 16 + frc) * S_LDT + j0);
;             hacc[nt] = mfma16(af, b, hacc[nt]);
;           }
;         }
; #pragma unroll
;         for (int nt = 0; nt < 8; ++nt)
; #pragma unroll
;           for (int j = 0; j < 4; ++j) myH[(fqc * 4 + j) * S_LDB + nt * 16 + frc] = f2bf(hacc[nt][j]);
;       }
;       lds_barrier();
;       if (tid < 64) {
;         float sm = 0.f;
; #pragma unroll
;         for (int ww = 0; ww < 8; ++ww) sm += sSq[ww * 64 + tid];
;         ssqp[(size_t)(r0 + tid) * 16 + g * 4 + hp] = sm;
;       }
	v_mfma_f32_16x16x32_bf16 v[12:15], v[100:103], v[216:219], v[12:15]
	s_waitcnt lgkmcnt(2)
	v_mfma_f32_16x16x32_bf16 v[16:19], v[100:103], v[220:223], v[16:19]
	s_waitcnt lgkmcnt(1)
	v_mfma_f32_16x16x32_bf16 v[4:7], v[100:103], v[224:227], v[4:7]
	s_waitcnt lgkmcnt(0)
	v_mfma_f32_16x16x32_bf16 v[8:11], v[100:103], v[236:239], v[8:11]
	v_bfe_u32 v80, v28, 16, 1
	v_lshlrev_b32_e32 v81, 1, v92
	v_add3_u32 v80, v28, v80, s96
	v_add3_u32 v0, s9, v81, v0
	ds_write_b16_d16_hi v0, v80
	v_bfe_u32 v80, v29, 16, 1
	v_add3_u32 v80, v29, v80, s96
	ds_write_b16_d16_hi v0, v80 offset:272
	v_bfe_u32 v80, v30, 16, 1
	v_add3_u32 v80, v30, v80, s96
	ds_write_b16_d16_hi v0, v80 offset:544
	v_bfe_u32 v80, v31, 16, 1
	v_add3_u32 v80, v31, v80, s96
	ds_write_b16_d16_hi v0, v80 offset:816
	v_bfe_u32 v80, v32, 16, 1
	v_add3_u32 v80, v32, v80, s96
	ds_write_b16_d16_hi v0, v80 offset:32
	v_bfe_u32 v80, v33, 16, 1
	v_add3_u32 v80, v33, v80, s96
	ds_write_b16_d16_hi v0, v80 offset:304
	v_bfe_u32 v80, v34, 16, 1
	v_add3_u32 v80, v34, v80, s96
	ds_write_b16_d16_hi v0, v80 offset:576
	v_bfe_u32 v80, v35, 16, 1
	v_add3_u32 v80, v35, v80, s96
	ds_write_b16_d16_hi v0, v80 offset:848
	v_bfe_u32 v80, v20, 16, 1
	v_add3_u32 v80, v20, v80, s96
	ds_write_b16_d16_hi v0, v80 offset:64
	v_bfe_u32 v80, v21, 16, 1
	v_add3_u32 v80, v21, v80, s96
	ds_write_b16_d16_hi v0, v80 offset:336
	v_bfe_u32 v80, v22, 16, 1
	v_add3_u32 v80, v22, v80, s96
	ds_write_b16_d16_hi v0, v80 offset:608
	v_bfe_u32 v80, v23, 16, 1
	v_add3_u32 v80, v23, v80, s96
	ds_write_b16_d16_hi v0, v80 offset:880
	v_bfe_u32 v80, v24, 16, 1
	v_add3_u32 v80, v24, v80, s96
	ds_write_b16_d16_hi v0, v80 offset:96
	v_bfe_u32 v80, v25, 16, 1
	v_add3_u32 v80, v25, v80, s96
	ds_write_b16_d16_hi v0, v80 offset:368
	v_bfe_u32 v80, v26, 16, 1
	v_add3_u32 v80, v26, v80, s96
	ds_write_b16_d16_hi v0, v80 offset:640
	v_bfe_u32 v80, v27, 16, 1
	v_add3_u32 v80, v27, v80, s96
	ds_write_b16_d16_hi v0, v80 offset:912
	v_bfe_u32 v80, v12, 16, 1
	v_add3_u32 v80, v12, v80, s96
	ds_write_b16_d16_hi v0, v80 offset:128
	v_bfe_u32 v80, v13, 16, 1
	v_add3_u32 v80, v13, v80, s96
	ds_write_b16_d16_hi v0, v80 offset:400
	v_bfe_u32 v80, v14, 16, 1
	v_add3_u32 v80, v14, v80, s96
	ds_write_b16_d16_hi v0, v80 offset:672
	v_bfe_u32 v80, v15, 16, 1
	v_add3_u32 v80, v15, v80, s96
	ds_write_b16_d16_hi v0, v80 offset:944
	v_bfe_u32 v80, v16, 16, 1
	v_add3_u32 v80, v16, v80, s96
	ds_write_b16_d16_hi v0, v80 offset:160
	v_bfe_u32 v80, v17, 16, 1
	v_add3_u32 v80, v17, v80, s96
	ds_write_b16_d16_hi v0, v80 offset:432
	v_bfe_u32 v80, v18, 16, 1
	v_add3_u32 v80, v18, v80, s96
	ds_write_b16_d16_hi v0, v80 offset:704
	v_bfe_u32 v80, v19, 16, 1
	v_add3_u32 v80, v19, v80, s96
	ds_write_b16_d16_hi v0, v80 offset:976
	v_bfe_u32 v80, v4, 16, 1
	v_add3_u32 v80, v4, v80, s96
	ds_write_b16_d16_hi v0, v80 offset:192
	v_bfe_u32 v80, v5, 16, 1
	v_add3_u32 v80, v5, v80, s96
	ds_write_b16_d16_hi v0, v80 offset:464
	v_bfe_u32 v80, v6, 16, 1
	v_add3_u32 v80, v6, v80, s96
	ds_write_b16_d16_hi v0, v80 offset:736
	v_bfe_u32 v80, v7, 16, 1
	v_add3_u32 v80, v7, v80, s96
	ds_write_b16_d16_hi v0, v80 offset:1008
	v_bfe_u32 v80, v8, 16, 1
	v_add3_u32 v80, v8, v80, s96
	ds_write_b16_d16_hi v0, v80 offset:224
	v_bfe_u32 v80, v9, 16, 1
	v_add3_u32 v80, v9, v80, s96
	ds_write_b16_d16_hi v0, v80 offset:496
	v_bfe_u32 v80, v10, 16, 1
	v_add3_u32 v80, v10, v80, s96
	ds_write_b16_d16_hi v0, v80 offset:768
	v_bfe_u32 v80, v11, 16, 1
	v_add3_u32 v80, v11, v80, s96
	ds_write_b16_d16_hi v0, v80 offset:1040
	s_waitcnt lgkmcnt(0)
	s_barrier
	s_and_saveexec_b64 s[34:35], s[14:15]
	s_cbranch_execz .LBB0_414
	ds_read2st64_b32 v[80:81], v204 offset1:1
	s_waitcnt lgkmcnt(0)
	v_add_f32_e32 v0, 0, v80
	v_add_f32_e32 v0, v0, v81
	ds_read2st64_b32 v[80:81], v204 offset0:2 offset1:3
	s_waitcnt lgkmcnt(0)
	v_add_f32_e32 v0, v0, v80
	v_add_f32_e32 v0, v0, v81
	ds_read2st64_b32 v[80:81], v204 offset0:4 offset1:5
	s_waitcnt lgkmcnt(0)
	v_add_f32_e32 v0, v0, v80
	v_add_f32_e32 v0, v0, v81
	ds_read2st64_b32 v[80:81], v204 offset0:6 offset1:7
	s_waitcnt lgkmcnt(0)
	v_add_f32_e32 v0, v0, v80
	v_add_u32_e32 v80, s48, v113
	v_add_f32_e32 v0, v0, v81
	v_ashrrev_i32_e32 v81, 31, v80
	v_lshlrev_b64 v[80:81], 6, v[80:81]
	v_lshl_add_u64 v[80:81], s[80:81], 0, v[80:81]
	global_store_dword v[80:81], v0, off
	s_branch .LBB0_414
